# adds P4 and P7: nt on the final output stores and relaxed first waits (peeled first iteration)
# speedup vs baseline: 1.0066x; 1.0024x over previous
.LBB0_652:
	s_add_u32 s81, s26, 0x102000
	s_addc_u32 s82, s27, 0
	s_add_u32 s48, s26, 0x2200000
	s_addc_u32 s49, s27, 0
	s_add_u32 s83, s26, 0x10000
	s_mov_b64 s[50:51], 0x80
	s_addc_u32 s84, s27, 0
	s_and_b32 s10, s6, 3
	s_add_i32 m0, s77, 0x18000
	v_lshl_add_u64 v[8:9], v[8:9], 0, s[50:51]
	s_lshl_b32 s85, s5, 6
	s_lshl_b32 s11, s5, 13
	s_lshl_b32 s30, s10, 12
	s_waitcnt vmcnt(2)
	s_barrier
	global_load_lds_dwordx4 v[8:9], off
	v_lshl_add_u64 v[6:7], v[6:7], 0, s[50:51]
	s_add_i32 m0, s77, 0x1a000
	s_add_i32 s86, s77, 0x8000
	s_add_i32 s87, s77, 0xa000
	global_load_lds_dwordx4 v[6:7], off
	v_lshl_add_u64 v[2:3], v[2:3], 0, s[50:51]
	s_mov_b32 m0, s86
	s_add_u32 s6, s8, 0x40080
	global_load_lds_dwordx4 v[2:3], off
	v_lshl_add_u64 v[2:3], v[4:5], 0, s[50:51]
	s_mov_b32 m0, s87
	s_addc_u32 s7, s9, 0
	global_load_lds_dwordx4 v[2:3], off
	s_add_i32 m0, s77, 0x1c000
	v_lshl_add_u64 v[2:3], s[6:7], 0, v[194:195]
	global_load_lds_dwordx4 v[2:3], off
	v_lshl_add_u64 v[2:3], s[6:7], 0, v[196:197]
	s_add_i32 m0, s77, 0x1e000
	v_bfe_u32 v229, v10, 4, 2
	global_load_lds_dwordx4 v[2:3], off
	v_and_b32_e32 v228, 15, v10
	v_lshlrev_b32_e32 v2, 4, v229
	v_lshlrev_b32_e32 v3, 2, v10
	v_lshl_or_b32 v2, v228, 6, v2
	v_and_b32_e32 v3, 32, v3
	v_bitop3_b32 v4, v2, s11, v3 bitop3:0xde
	v_bitop3_b32 v230, v2, s30, v3 bitop3:0xde
	v_lshlrev_b32_e32 v2, 14, v11
	v_and_b32_e32 v2, 0xffff8000, v2
	v_lshl_add_u32 v2, v12, 11, v2
	v_and_b32_e32 v3, 1, v11
	v_lshl_or_b32 v2, v3, 6, v2
	s_cmpk_lt_u32 s4, 0x100
	v_lshl_add_u32 v198, v13, 1, v2
	v_lshlrev_b32_e32 v2, 14, v14
	s_cselect_b64 s[52:53], -1, 0
	s_lshl_b32 s4, s10, 2
	v_and_b32_e32 v2, 0xffff8000, v2
	s_waitcnt vmcnt(6)
	s_add_i32 s92, s4, 0
	s_lshl_b32 s4, s5, 8
	v_lshl_add_u32 v2, v15, 11, v2
	v_and_b32_e32 v3, 1, v14
	s_lshl_b32 s88, s10, 6
	s_add_i32 s93, s4, 0
	v_lshl_or_b32 v2, v3, 6, v2
	s_add_i32 s94, 0, 0x10000
	s_add_i32 s95, 0, 0x14000
	s_lshl_b32 s89, s10, 7
	s_ashr_i32 s90, s3, 31
	s_ashr_i32 s91, s2, 31
	s_add_i32 s92, s92, 0x20000
	s_add_i32 s93, s93, 0x21000
	v_mov_b32_e32 v199, v195
	v_lshl_add_u32 v200, v16, 1, v2
	v_mov_b32_e32 v201, v195
	v_mov_b64_e32 v[202:203], 0x400
	v_mov_b64_e32 v[204:205], 0x3ff
	v_add_u32_e32 v231, s94, v230
	v_add_u32_e32 v232, s95, v230
	v_add_u32_e32 v233, 0, v4
	s_lshl_b32 s42, s88, 2
	s_add_i32 s96, 0, 0x21400
	v_mov_b32_e32 v234, 0x358637bd
	v_mov_b32_e32 v235, 0x260
	s_movk_i32 s97, 0x90
	v_mov_b64_e32 v[206:207], 0x1e8481
	s_mov_b32 s98, 0
	s_mov_b32 s30, s43
	s_barrier
	s_branch .LBB0_655

.LBB0_661:
	s_ashr_i32 s57, s56, 31
	s_lshl_b64 s[6:7], s[56:57], 19
	s_add_u32 s58, s44, s6
	s_addc_u32 s59, s45, s7
	s_and_b64 s[6:7], s[4:5], exec
	s_cselect_b32 s31, s59, s1
	s_cselect_b32 s57, s58, s0
	s_ashr_i32 s55, s54, 31
	s_lshl_b64 s[6:7], s[54:55], 19
	s_add_u32 s60, s38, s6
	s_addc_u32 s61, s39, s7
	s_and_b64 s[6:7], s[4:5], exec
	s_cselect_b32 s55, s61, s9
	s_cselect_b32 s63, s60, s8
	s_add_u32 s0, s0, 0x40080
	s_addc_u32 s1, s1, 0
	s_add_u32 s65, s8, 0x100
	v_mov_b32_e32 v2, 0
	s_addc_u32 s66, s9, 0
	s_mov_b32 s67, -2
	v_mov_b32_e32 v3, v2
	v_mov_b32_e32 v4, v2
	v_mov_b32_e32 v5, v2
	v_mov_b32_e32 v6, v2
	v_mov_b32_e32 v7, v2
	v_mov_b32_e32 v8, v2
	v_mov_b32_e32 v9, v2
	v_mov_b32_e32 v18, v2
	v_mov_b32_e32 v19, v2
	v_mov_b32_e32 v20, v2
	v_mov_b32_e32 v21, v2
	v_mov_b32_e32 v22, v2
	v_mov_b32_e32 v23, v2
	v_mov_b32_e32 v24, v2
	v_mov_b32_e32 v25, v2
	v_mov_b32_e32 v34, v2
	v_mov_b32_e32 v35, v2
	v_mov_b32_e32 v36, v2
	v_mov_b32_e32 v37, v2
	v_mov_b32_e32 v38, v2
	v_mov_b32_e32 v39, v2
	v_mov_b32_e32 v40, v2
	v_mov_b32_e32 v41, v2
	v_mov_b32_e32 v50, v2
	v_mov_b32_e32 v51, v2
	v_mov_b32_e32 v52, v2
	v_mov_b32_e32 v53, v2
	v_mov_b32_e32 v54, v2
	v_mov_b32_e32 v55, v2
	v_mov_b32_e32 v56, v2
	v_mov_b32_e32 v57, v2
	v_mov_b32_e32 v10, v2
	v_mov_b32_e32 v11, v2
	v_mov_b32_e32 v12, v2
	v_mov_b32_e32 v13, v2
	v_mov_b32_e32 v14, v2
	v_mov_b32_e32 v15, v2
	v_mov_b32_e32 v16, v2
	v_mov_b32_e32 v17, v2
	v_mov_b32_e32 v26, v2
	v_mov_b32_e32 v27, v2
	v_mov_b32_e32 v28, v2
	v_mov_b32_e32 v29, v2
	v_mov_b32_e32 v30, v2
	v_mov_b32_e32 v31, v2
	v_mov_b32_e32 v32, v2
	v_mov_b32_e32 v33, v2
	v_mov_b32_e32 v42, v2
	v_mov_b32_e32 v43, v2
	v_mov_b32_e32 v44, v2
	v_mov_b32_e32 v45, v2
	v_mov_b32_e32 v46, v2
	v_mov_b32_e32 v47, v2
	v_mov_b32_e32 v48, v2
	v_mov_b32_e32 v49, v2
	v_mov_b32_e32 v62, v2
	v_mov_b32_e32 v63, v2
	v_mov_b32_e32 v64, v2
	v_mov_b32_e32 v65, v2
	v_mov_b32_e32 v58, v2
	v_mov_b32_e32 v59, v2
	v_mov_b32_e32 v60, v2
	v_mov_b32_e32 v61, v2
	v_mov_b32_e32 v66, v2
	v_mov_b32_e32 v67, v2
	v_mov_b32_e32 v68, v2
	v_mov_b32_e32 v69, v2
	v_mov_b32_e32 v70, v2
	v_mov_b32_e32 v71, v2
	v_mov_b32_e32 v72, v2
	v_mov_b32_e32 v73, v2
	v_mov_b32_e32 v82, v2
	v_mov_b32_e32 v83, v2
	v_mov_b32_e32 v84, v2
	v_mov_b32_e32 v85, v2
	v_mov_b32_e32 v86, v2
	v_mov_b32_e32 v87, v2
	v_mov_b32_e32 v88, v2
	v_mov_b32_e32 v89, v2
	s_cmp_eq_u32 s98, -1
	s_cbranch_scc1 .Lrwp4_prelaxed
	s_waitcnt vmcnt(0)
.Lrwp4_pdone:
	v_mov_b32_e32 v98, v2
	v_mov_b32_e32 v99, v2
	v_mov_b32_e32 v100, v2
	v_mov_b32_e32 v101, v2
	v_mov_b32_e32 v102, v2
	v_mov_b32_e32 v103, v2
	v_mov_b32_e32 v104, v2
	v_mov_b32_e32 v105, v2
	v_mov_b32_e32 v114, v2
	v_mov_b32_e32 v115, v2
	v_mov_b32_e32 v116, v2
	v_mov_b32_e32 v117, v2
	v_mov_b32_e32 v118, v2
	v_mov_b32_e32 v119, v2
	v_mov_b32_e32 v120, v2
	v_mov_b32_e32 v121, v2
	v_mov_b32_e32 v74, v2
	v_mov_b32_e32 v75, v2
	v_mov_b32_e32 v76, v2
	v_mov_b32_e32 v77, v2
	v_mov_b32_e32 v78, v2
	v_mov_b32_e32 v79, v2
	v_mov_b32_e32 v80, v2
	v_mov_b32_e32 v81, v2
	v_mov_b32_e32 v90, v2
	v_mov_b32_e32 v91, v2
	v_mov_b32_e32 v92, v2
	v_mov_b32_e32 v93, v2
	v_mov_b32_e32 v94, v2
	v_mov_b32_e32 v95, v2
	v_mov_b32_e32 v96, v2
	v_mov_b32_e32 v97, v2
	v_mov_b32_e32 v106, v2
	v_mov_b32_e32 v107, v2
	v_mov_b32_e32 v108, v2
	v_mov_b32_e32 v109, v2
	v_mov_b32_e32 v110, v2
	v_mov_b32_e32 v111, v2
	v_mov_b32_e32 v112, v2
	v_mov_b32_e32 v113, v2
	v_mov_b32_e32 v122, v2
	v_mov_b32_e32 v123, v2
	v_mov_b32_e32 v124, v2
	v_mov_b32_e32 v125, v2
	v_mov_b32_e32 v126, v2
	v_mov_b32_e32 v127, v2
	v_mov_b32_e32 v128, v2
	v_mov_b32_e32 v129, v2
	s_cmp_lg_u32 s98, 0
	s_cbranch_scc1 .Lrwp4_first

.Lrwp4_exit:
	s_and_b64 vcc, exec, s[52:53]
	s_cbranch_vccz .LBB0_665
	s_barrier

.LBB0_707:
	s_or_b64 exec, exec, s[8:9]
	s_add_u32 s7, s68, s66
	s_waitcnt lgkmcnt(0)
	s_barrier
	v_lshl_add_u32 v2, v237, 2, s93
	s_addc_u32 s8, s69, s67
	s_or_b32 s0, s55, s88
	ds_read2_b32 v[88:89], v2 offset1:16
	ds_read2_b32 v[86:87], v2 offset0:32 offset1:48
	ds_read2_b32 v[84:85], v2 offset0:128 offset1:144
	ds_read2_b32 v[66:67], v2 offset0:160 offset1:176
	v_add_u32_e32 v2, s0, v239
	s_add_u32 s0, s7, 0x4000
	s_waitcnt vmcnt(2)
	v_ashrrev_i32_e32 v3, 31, v2
	s_addc_u32 s1, s8, 0
	s_waitcnt vmcnt(1)
	v_lshlrev_b64 v[4:5], 2, v[2:3]
	s_waitcnt lgkmcnt(0)
	v_lshl_add_u64 v[8:9], s[0:1], 0, v[4:5]
	global_load_dwordx4 v[74:77], v[8:9], off
	v_add_u32_e32 v8, 16, v2
	v_ashrrev_i32_e32 v9, 31, v8
	v_lshlrev_b64 v[8:9], 2, v[8:9]
	v_lshl_add_u64 v[10:11], s[0:1], 0, v[8:9]
	global_load_dwordx4 v[92:95], v[10:11], off
	v_add_u32_e32 v10, 32, v2
	v_ashrrev_i32_e32 v11, 31, v10
	v_add_u32_e32 v2, 48, v2
	v_lshlrev_b64 v[78:79], 2, v[10:11]
	v_ashrrev_i32_e32 v3, 31, v2
	s_waitcnt vmcnt(2)
	v_lshl_add_u64 v[6:7], s[16:17], 0, v[4:5]
	v_lshl_add_u64 v[10:11], s[0:1], 0, v[78:79]
	v_lshlrev_b64 v[2:3], 2, v[2:3]
	global_load_dwordx4 v[70:73], v[6:7], off
	global_load_dwordx4 v[130:133], v[10:11], off
	v_lshl_add_u64 v[10:11], s[0:1], 0, v[2:3]
	global_load_dwordx4 v[134:137], v[10:11], off
	global_load_dwordx4 v[138:141], v[6:7], off offset:64
	global_load_dwordx4 v[142:145], v[6:7], off offset:128
	global_load_dwordx4 v[152:155], v[6:7], off offset:192
	s_add_u32 s0, s7, 0x3000
	s_addc_u32 s1, s8, 0
	v_lshl_add_u64 v[4:5], s[0:1], 0, v[4:5]
	global_load_dwordx4 v[14:17], v[4:5], off
	v_lshl_add_u64 v[4:5], s[0:1], 0, v[8:9]
	global_load_dwordx4 v[10:13], v[4:5], off
	v_lshl_add_u64 v[4:5], s[0:1], 0, v[78:79]
	global_load_dwordx4 v[6:9], v[4:5], off
	v_lshl_add_u64 v[2:3], s[0:1], 0, v[2:3]
	global_load_dwordx4 v[2:5], v[2:3], off
	s_mulk_i32 s6, 0x900
	v_lshrrev_b32_e32 v68, 3, v68
	v_lshlrev_b32_e32 v69, 4, v238
	s_add_i32 s0, s6, 0
	v_mul_lo_u32 v78, v237, s97
	v_lshlrev_b32_e32 v79, 3, v236
	v_or_b32_e32 v100, s31, v68
	v_and_b32_e32 v101, 0x70, v69
	v_mul_u32_u24_e32 v68, 0x90, v68
	s_add_i32 s0, s0, 0x22000
	v_add3_u32 v91, s0, v78, v79
	v_add3_u32 v90, s0, v68, v101
	v_cvt_pk_bf16_f32 v68, v222, v223
	v_cvt_pk_bf16_f32 v69, v214, v215
	ds_write_b64 v91, v[68:69]
	v_cvt_pk_bf16_f32 v68, v220, v221
	v_cvt_pk_bf16_f32 v69, v212, v213
	ds_write_b64 v91, v[68:69] offset:32
	v_cvt_pk_bf16_f32 v68, v218, v219
	v_cvt_pk_bf16_f32 v69, v210, v211
	ds_write_b64 v91, v[68:69] offset:64
	v_cvt_pk_bf16_f32 v96, v216, v217
	v_cvt_pk_bf16_f32 v97, v208, v209
	ds_write_b64 v91, v[96:97] offset:96
	s_lshl_b32 s1, s62, 9
	s_or_b32 s0, s1, s89
	s_andn2_b64 vcc, exec, s[4:5]
	s_waitcnt vmcnt(11)
	v_pk_add_f32 v[68:69], v[76:77], 1.0 op_sel_hi:[1,0]
	v_pk_add_f32 v[74:75], v[74:75], 1.0 op_sel_hi:[1,0]
	s_waitcnt vmcnt(9)
	v_pk_mul_f32 v[80:81], v[72:73], v[68:69]
	v_pk_mul_f32 v[82:83], v[70:71], v[74:75]
	v_pk_add_f32 v[68:69], v[94:95], 1.0 op_sel_hi:[1,0]
	v_pk_add_f32 v[70:71], v[92:93], 1.0 op_sel_hi:[1,0]
	s_waitcnt vmcnt(7)
	v_pk_add_f32 v[94:95], v[134:135], 1.0 op_sel_hi:[1,0]
	s_waitcnt vmcnt(6)
	v_pk_mul_f32 v[78:79], v[138:139], v[70:71]
	s_waitcnt vmcnt(4)
	v_pk_mul_f32 v[70:71], v[152:153], v[94:95]
	ds_read_b128 v[94:97], v90
	v_pk_add_f32 v[72:73], v[132:133], 1.0 op_sel_hi:[1,0]
	v_pk_add_f32 v[74:75], v[130:131], 1.0 op_sel_hi:[1,0]
	ds_read_b128 v[130:133], v90 offset:1152
	v_pk_add_f32 v[92:93], v[136:137], 1.0 op_sel_hi:[1,0]
	v_pk_mul_f32 v[76:77], v[140:141], v[68:69]
	v_pk_mul_f32 v[68:69], v[154:155], v[92:93]
	v_or_b32_e32 v92, s0, v101
	v_lshl_add_u32 v92, v100, 11, v92
	s_waitcnt lgkmcnt(1)
	global_store_dwordx4 v92, v[94:97], s[40:41] nt
	s_bitset1_b32 s98, 0
	v_add_u32_e32 v93, 0x4000, v92
	s_waitcnt lgkmcnt(0)
	global_store_dwordx4 v93, v[130:133], s[40:41] nt
	s_bitset1_b32 s98, 1
	v_pk_mul_f32 v[94:95], v[222:223], v[88:89] op_sel_hi:[1,0]
	v_pk_mul_f32 v[96:97], v[214:215], v[88:89] op_sel_hi:[1,0]
	s_waitcnt vmcnt(5)
	v_pk_fma_f32 v[94:95], v[94:95], v[82:83], v[14:15]
	v_pk_fma_f32 v[96:97], v[96:97], v[80:81], v[16:17]
	v_cvt_pk_bf16_f32 v94, v94, v95
	v_pk_mul_f32 v[74:75], v[142:143], v[74:75]
	v_cvt_pk_bf16_f32 v95, v96, v97
	ds_write_b64 v91, v[94:95]
	v_pk_mul_f32 v[94:95], v[220:221], v[88:89] op_sel_hi:[1,0]
	v_pk_mul_f32 v[96:97], v[212:213], v[88:89] op_sel_hi:[1,0]
	s_waitcnt vmcnt(4)
	v_pk_fma_f32 v[94:95], v[94:95], v[78:79], v[10:11]
	v_pk_fma_f32 v[96:97], v[96:97], v[76:77], v[12:13]
	v_cvt_pk_bf16_f32 v94, v94, v95
	v_pk_mul_f32 v[72:73], v[144:145], v[72:73]
	v_cvt_pk_bf16_f32 v95, v96, v97
	ds_write_b64 v91, v[94:95] offset:32
	v_pk_mul_f32 v[94:95], v[218:219], v[88:89] op_sel_hi:[1,0]
	v_pk_mul_f32 v[96:97], v[210:211], v[88:89] op_sel_hi:[1,0]
	s_waitcnt vmcnt(3)
	v_pk_fma_f32 v[94:95], v[94:95], v[74:75], v[6:7]
	v_pk_fma_f32 v[96:97], v[96:97], v[72:73], v[8:9]
	v_cvt_pk_bf16_f32 v94, v94, v95
	v_add_u32_e32 v100, 0xc000, v92
	v_cvt_pk_bf16_f32 v95, v96, v97
	ds_write_b64 v91, v[94:95] offset:64
	v_pk_mul_f32 v[94:95], v[216:217], v[88:89] op_sel_hi:[1,0]
	v_pk_mul_f32 v[96:97], v[208:209], v[88:89] op_sel_hi:[1,0]
	s_waitcnt vmcnt(2)
	v_pk_fma_f32 v[94:95], v[94:95], v[70:71], v[2:3]
	v_pk_fma_f32 v[96:97], v[96:97], v[68:69], v[4:5]
	v_cvt_pk_bf16_f32 v94, v94, v95
	v_mov_b32_e32 v88, v89
	v_cvt_pk_bf16_f32 v95, v96, v97
	ds_write_b64 v91, v[94:95] offset:96
	ds_read_b128 v[94:97], v90
	ds_read_b128 v[130:133], v90 offset:1152
	s_waitcnt lgkmcnt(1)
	global_store_dwordx4 v92, v[94:97], s[18:19] nt
	s_bitset1_b32 s98, 2
	s_waitcnt lgkmcnt(0)
	global_store_dwordx4 v93, v[130:133], s[18:19] nt
	s_bitset1_b32 s98, 3
	v_cvt_pk_bf16_f32 v94, v190, v191
	v_cvt_pk_bf16_f32 v95, v192, v193
	ds_write_b64 v91, v[94:95]
	v_cvt_pk_bf16_f32 v94, v186, v187
	v_cvt_pk_bf16_f32 v95, v188, v189
	ds_write_b64 v91, v[94:95] offset:32
	v_cvt_pk_bf16_f32 v94, v182, v183
	v_cvt_pk_bf16_f32 v95, v184, v185
	ds_write_b64 v91, v[94:95] offset:64
	v_cvt_pk_bf16_f32 v94, v178, v179
	v_cvt_pk_bf16_f32 v95, v180, v181
	ds_write_b64 v91, v[94:95] offset:96
	ds_read_b128 v[94:97], v90
	ds_read_b128 v[130:133], v90 offset:1152
	v_add_u32_e32 v93, 0x8000, v92
	s_mov_b64 s[0:1], -1
	s_waitcnt lgkmcnt(1)
	global_store_dwordx4 v93, v[94:97], s[40:41] nt
	s_bitset1_b32 s98, 4
	s_waitcnt lgkmcnt(0)
	global_store_dwordx4 v100, v[130:133], s[40:41] nt
	s_bitset1_b32 s98, 5
	v_pk_mul_f32 v[94:95], v[190:191], v[88:89] op_sel_hi:[1,0]
	v_pk_mul_f32 v[96:97], v[192:193], v[88:89] op_sel_hi:[1,0]
	v_pk_fma_f32 v[94:95], v[94:95], v[82:83], v[14:15]
	v_pk_fma_f32 v[96:97], v[96:97], v[80:81], v[16:17]
	v_cvt_pk_bf16_f32 v94, v94, v95
	s_nop 0
	v_cvt_pk_bf16_f32 v95, v96, v97
	ds_write_b64 v91, v[94:95]
	v_pk_mul_f32 v[94:95], v[186:187], v[88:89] op_sel_hi:[1,0]
	v_pk_mul_f32 v[96:97], v[188:189], v[88:89] op_sel_hi:[1,0]
	v_pk_fma_f32 v[94:95], v[94:95], v[78:79], v[10:11]
	v_pk_fma_f32 v[96:97], v[96:97], v[76:77], v[12:13]
	v_cvt_pk_bf16_f32 v94, v94, v95
	s_nop 0
	v_cvt_pk_bf16_f32 v95, v96, v97
	ds_write_b64 v91, v[94:95] offset:32
	v_pk_mul_f32 v[94:95], v[182:183], v[88:89] op_sel_hi:[1,0]
	v_pk_mul_f32 v[96:97], v[184:185], v[88:89] op_sel_hi:[1,0]
	v_pk_fma_f32 v[94:95], v[94:95], v[74:75], v[6:7]
	v_pk_fma_f32 v[96:97], v[96:97], v[72:73], v[8:9]
	v_cvt_pk_bf16_f32 v94, v94, v95
	s_nop 0
	v_cvt_pk_bf16_f32 v95, v96, v97
	ds_write_b64 v91, v[94:95] offset:64
	v_pk_mul_f32 v[94:95], v[178:179], v[88:89] op_sel_hi:[1,0]
	v_pk_mul_f32 v[88:89], v[180:181], v[88:89] op_sel_hi:[1,0]
	v_pk_fma_f32 v[94:95], v[94:95], v[70:71], v[2:3]
	v_pk_fma_f32 v[88:89], v[88:89], v[68:69], v[4:5]
	v_cvt_pk_bf16_f32 v94, v94, v95
	s_nop 0
	v_cvt_pk_bf16_f32 v95, v88, v89
	ds_write_b64 v91, v[94:95] offset:96
	ds_read_b128 v[94:97], v90
	ds_read_b128 v[130:133], v90 offset:1152
	s_waitcnt lgkmcnt(1)
	global_store_dwordx4 v93, v[94:97], s[18:19] nt
	s_bitset1_b32 s98, 6
	s_waitcnt lgkmcnt(0)
	global_store_dwordx4 v100, v[130:133], s[18:19] nt
	s_bitset1_b32 s98, 7
	v_cvt_pk_bf16_f32 v88, v174, v175
	v_cvt_pk_bf16_f32 v89, v176, v177
	ds_write_b64 v91, v[88:89]
	v_cvt_pk_bf16_f32 v88, v170, v171
	v_cvt_pk_bf16_f32 v89, v172, v173
	ds_write_b64 v91, v[88:89] offset:32
	v_cvt_pk_bf16_f32 v88, v166, v167
	v_cvt_pk_bf16_f32 v89, v168, v169
	ds_write_b64 v91, v[88:89] offset:64
	v_cvt_pk_bf16_f32 v88, v162, v163
	v_cvt_pk_bf16_f32 v89, v164, v165
	ds_write_b64 v91, v[88:89] offset:96
	ds_read_b128 v[94:97], v90
	ds_read_b128 v[130:133], v90 offset:1152
	v_add_u32_e32 v93, 0x10000, v92
	v_add_u32_e32 v100, 0x14000, v92
	v_pk_mul_f32 v[88:89], v[174:175], v[86:87] op_sel_hi:[1,0]
	s_waitcnt lgkmcnt(1)
	global_store_dwordx4 v93, v[94:97], s[40:41] nt
	s_bitset1_b32 s98, 8
	s_waitcnt lgkmcnt(0)
	global_store_dwordx4 v100, v[130:133], s[40:41] nt
	s_bitset1_b32 s98, 9
	v_pk_fma_f32 v[88:89], v[88:89], v[82:83], v[14:15]
	v_pk_mul_f32 v[94:95], v[176:177], v[86:87] op_sel_hi:[1,0]
	v_cvt_pk_bf16_f32 v88, v88, v89
	s_nop 0
	v_pk_fma_f32 v[94:95], v[94:95], v[80:81], v[16:17]
	s_nop 0
	v_cvt_pk_bf16_f32 v89, v94, v95
	ds_write_b64 v91, v[88:89]
	v_pk_mul_f32 v[88:89], v[170:171], v[86:87] op_sel_hi:[1,0]
	v_pk_mul_f32 v[94:95], v[172:173], v[86:87] op_sel_hi:[1,0]
	v_pk_fma_f32 v[88:89], v[88:89], v[78:79], v[10:11]
	v_pk_fma_f32 v[94:95], v[94:95], v[76:77], v[12:13]
	v_cvt_pk_bf16_f32 v88, v88, v89
	s_nop 0
	v_cvt_pk_bf16_f32 v89, v94, v95
	ds_write_b64 v91, v[88:89] offset:32
	v_pk_mul_f32 v[88:89], v[166:167], v[86:87] op_sel_hi:[1,0]
	v_pk_mul_f32 v[94:95], v[168:169], v[86:87] op_sel_hi:[1,0]
	v_pk_fma_f32 v[88:89], v[88:89], v[74:75], v[6:7]
	v_pk_fma_f32 v[94:95], v[94:95], v[72:73], v[8:9]
	v_cvt_pk_bf16_f32 v88, v88, v89
	s_nop 0
	v_cvt_pk_bf16_f32 v89, v94, v95
	ds_write_b64 v91, v[88:89] offset:64
	v_pk_mul_f32 v[88:89], v[162:163], v[86:87] op_sel_hi:[1,0]
	v_pk_mul_f32 v[94:95], v[164:165], v[86:87] op_sel_hi:[1,0]
	v_pk_fma_f32 v[88:89], v[88:89], v[70:71], v[2:3]
	v_pk_fma_f32 v[94:95], v[94:95], v[68:69], v[4:5]
	v_cvt_pk_bf16_f32 v88, v88, v89
	v_mov_b32_e32 v86, v87
	v_cvt_pk_bf16_f32 v89, v94, v95
	ds_write_b64 v91, v[88:89] offset:96
	ds_read_b128 v[94:97], v90
	ds_read_b128 v[130:133], v90 offset:1152
	s_waitcnt lgkmcnt(1)
	global_store_dwordx4 v93, v[94:97], s[18:19] nt
	s_bitset1_b32 s98, 10
	s_waitcnt lgkmcnt(0)
	global_store_dwordx4 v100, v[130:133], s[18:19] nt
	s_bitset1_b32 s98, 11
	v_cvt_pk_bf16_f32 v88, v128, v129
	v_cvt_pk_bf16_f32 v89, v120, v121
	ds_write_b64 v91, v[88:89]
	v_cvt_pk_bf16_f32 v88, v126, v127
	v_cvt_pk_bf16_f32 v89, v118, v119
	ds_write_b64 v91, v[88:89] offset:32
	v_cvt_pk_bf16_f32 v88, v124, v125
	v_cvt_pk_bf16_f32 v89, v116, v117
	ds_write_b64 v91, v[88:89] offset:64
	v_cvt_pk_bf16_f32 v88, v122, v123
	v_cvt_pk_bf16_f32 v89, v114, v115
	ds_write_b64 v91, v[88:89] offset:96
	ds_read_b128 v[94:97], v90
	ds_read_b128 v[130:133], v90 offset:1152
	v_add_u32_e32 v93, 0x18000, v92
	v_add_u32_e32 v100, 0x1c000, v92
	v_pk_mul_f32 v[88:89], v[128:129], v[86:87] op_sel_hi:[1,0]
	s_waitcnt lgkmcnt(1)
	global_store_dwordx4 v93, v[94:97], s[40:41] nt
	s_bitset1_b32 s98, 12
	s_waitcnt lgkmcnt(0)
	global_store_dwordx4 v100, v[130:133], s[40:41] nt
	s_bitset1_b32 s98, 13
	v_pk_fma_f32 v[88:89], v[88:89], v[82:83], v[14:15]
	v_pk_mul_f32 v[94:95], v[120:121], v[86:87] op_sel_hi:[1,0]
	v_cvt_pk_bf16_f32 v88, v88, v89
	s_nop 0
	v_pk_fma_f32 v[94:95], v[94:95], v[80:81], v[16:17]
	s_nop 0
	v_cvt_pk_bf16_f32 v89, v94, v95
	ds_write_b64 v91, v[88:89]
	v_pk_mul_f32 v[88:89], v[126:127], v[86:87] op_sel_hi:[1,0]
	v_pk_mul_f32 v[94:95], v[118:119], v[86:87] op_sel_hi:[1,0]
	v_pk_fma_f32 v[88:89], v[88:89], v[78:79], v[10:11]
	v_pk_fma_f32 v[94:95], v[94:95], v[76:77], v[12:13]
	v_cvt_pk_bf16_f32 v88, v88, v89
	s_nop 0
	v_cvt_pk_bf16_f32 v89, v94, v95
	ds_write_b64 v91, v[88:89] offset:32
	v_pk_mul_f32 v[88:89], v[124:125], v[86:87] op_sel_hi:[1,0]
	v_pk_mul_f32 v[94:95], v[116:117], v[86:87] op_sel_hi:[1,0]
	v_pk_fma_f32 v[88:89], v[88:89], v[74:75], v[6:7]
	v_pk_fma_f32 v[94:95], v[94:95], v[72:73], v[8:9]
	v_cvt_pk_bf16_f32 v88, v88, v89
	s_nop 0
	v_cvt_pk_bf16_f32 v89, v94, v95
	ds_write_b64 v91, v[88:89] offset:64
	v_pk_mul_f32 v[88:89], v[122:123], v[86:87] op_sel_hi:[1,0]
	v_pk_mul_f32 v[86:87], v[114:115], v[86:87] op_sel_hi:[1,0]
	v_pk_fma_f32 v[88:89], v[88:89], v[70:71], v[2:3]
	v_pk_fma_f32 v[86:87], v[86:87], v[68:69], v[4:5]
	v_cvt_pk_bf16_f32 v88, v88, v89
	s_nop 0
	v_cvt_pk_bf16_f32 v89, v86, v87
	ds_write_b64 v91, v[88:89] offset:96
	ds_read_b128 v[86:89], v90
	ds_read_b128 v[94:97], v90 offset:1152
	s_waitcnt lgkmcnt(1)
	global_store_dwordx4 v93, v[86:89], s[18:19] nt
	s_bitset1_b32 s98, 14
	s_waitcnt lgkmcnt(0)
	global_store_dwordx4 v100, v[94:97], s[18:19] nt
	s_bitset1_b32 s98, 15
	v_cvt_pk_bf16_f32 v86, v150, v151
	v_cvt_pk_bf16_f32 v87, v148, v149
	ds_write_b64 v91, v[86:87]
	v_cvt_pk_bf16_f32 v86, v62, v63
	v_cvt_pk_bf16_f32 v87, v64, v65
	ds_write_b64 v91, v[86:87] offset:32
	v_cvt_pk_bf16_f32 v86, v54, v55
	v_cvt_pk_bf16_f32 v87, v56, v57
	ds_write_b64 v91, v[86:87] offset:64
	v_cvt_pk_bf16_f32 v86, v146, v147
	v_cvt_pk_bf16_f32 v87, v52, v53
	ds_write_b64 v91, v[86:87] offset:96
	ds_read_b128 v[86:89], v90
	ds_read_b128 v[94:97], v90 offset:1152
	v_add_u32_e32 v93, 0x40000, v92
	v_add_u32_e32 v100, 0x44000, v92
	v_pk_mul_f32 v[62:63], v[62:63], v[84:85] op_sel_hi:[1,0]
	s_waitcnt lgkmcnt(1)
	global_store_dwordx4 v93, v[86:89], s[40:41] nt
	s_bitset1_b32 s98, 16
	v_pk_mul_f32 v[54:55], v[54:55], v[84:85] op_sel_hi:[1,0]
	s_waitcnt lgkmcnt(0)
	global_store_dwordx4 v100, v[94:97], s[40:41] nt
	s_bitset1_b32 s98, 17
	v_pk_mul_f32 v[86:87], v[150:151], v[84:85] op_sel_hi:[1,0]
	v_pk_mul_f32 v[88:89], v[148:149], v[84:85] op_sel_hi:[1,0]
	v_pk_fma_f32 v[86:87], v[86:87], v[82:83], v[14:15]
	v_pk_mul_f32 v[64:65], v[64:65], v[84:85] op_sel_hi:[1,0]
	v_pk_fma_f32 v[62:63], v[62:63], v[78:79], v[10:11]
	v_pk_mul_f32 v[56:57], v[56:57], v[84:85] op_sel_hi:[1,0]
	v_pk_fma_f32 v[54:55], v[54:55], v[74:75], v[6:7]
	v_pk_fma_f32 v[88:89], v[88:89], v[80:81], v[16:17]
	v_cvt_pk_bf16_f32 v86, v86, v87
	v_pk_fma_f32 v[64:65], v[64:65], v[76:77], v[12:13]
	v_cvt_pk_bf16_f32 v87, v88, v89
	ds_write_b64 v91, v[86:87]
	v_cvt_pk_bf16_f32 v62, v62, v63
	v_cvt_pk_bf16_f32 v63, v64, v65
	ds_write_b64 v91, v[62:63] offset:32
	v_pk_fma_f32 v[56:57], v[56:57], v[72:73], v[8:9]
	v_cvt_pk_bf16_f32 v54, v54, v55
	v_pk_mul_f32 v[52:53], v[52:53], v[84:85] op_sel_hi:[1,0]
	v_cvt_pk_bf16_f32 v55, v56, v57
	ds_write_b64 v91, v[54:55] offset:64
	v_pk_mul_f32 v[54:55], v[146:147], v[84:85] op_sel_hi:[1,0]
	v_pk_fma_f32 v[52:53], v[52:53], v[68:69], v[4:5]
	v_pk_fma_f32 v[54:55], v[54:55], v[70:71], v[2:3]
	v_add_u32_e32 v84, 0x48000, v92
	v_cvt_pk_bf16_f32 v54, v54, v55
	v_cvt_pk_bf16_f32 v55, v52, v53
	ds_write_b64 v91, v[54:55] offset:96
	ds_read_b128 v[52:55], v90
	ds_read_b128 v[62:65], v90 offset:1152
	s_waitcnt lgkmcnt(1)
	global_store_dwordx4 v93, v[52:55], s[18:19] nt
	s_bitset1_b32 s98, 18
	s_waitcnt lgkmcnt(0)
	global_store_dwordx4 v100, v[62:65], s[18:19] nt
	s_bitset1_b32 s98, 19
	v_cvt_pk_bf16_f32 v52, v110, v111
	v_cvt_pk_bf16_f32 v53, v112, v113
	ds_write_b64 v91, v[52:53]
	v_cvt_pk_bf16_f32 v52, v106, v107
	v_cvt_pk_bf16_f32 v53, v60, v61
	ds_write_b64 v91, v[52:53] offset:32
	v_cvt_pk_bf16_f32 v52, v102, v103
	v_cvt_pk_bf16_f32 v53, v58, v59
	ds_write_b64 v91, v[52:53] offset:64
	v_cvt_pk_bf16_f32 v52, v98, v99
	v_cvt_pk_bf16_f32 v53, v50, v51
	ds_write_b64 v91, v[52:53] offset:96
	ds_read_b128 v[52:55], v90
	ds_read_b128 v[62:65], v90 offset:1152
	v_add_u32_e32 v86, 0x4c000, v92
	s_waitcnt lgkmcnt(1)
	global_store_dwordx4 v84, v[52:55], s[40:41] nt
	s_bitset1_b32 s98, 20
	s_nop 1
	v_mov_b32_e32 v52, v85
	v_pk_mul_f32 v[54:55], v[110:111], v[52:53] op_sel_hi:[1,0]
	s_waitcnt lgkmcnt(0)
	global_store_dwordx4 v86, v[62:65], s[40:41] nt
	s_bitset1_b32 s98, 21
	v_pk_mul_f32 v[56:57], v[112:113], v[52:53] op_sel_hi:[1,0]
	v_pk_fma_f32 v[54:55], v[54:55], v[82:83], v[14:15]
	v_pk_fma_f32 v[56:57], v[56:57], v[80:81], v[16:17]
	v_cvt_pk_bf16_f32 v54, v54, v55
	v_pk_mul_f32 v[50:51], v[50:51], v[52:53] op_sel_hi:[1,0]
	v_cvt_pk_bf16_f32 v55, v56, v57
	ds_write_b64 v91, v[54:55]
	v_pk_mul_f32 v[54:55], v[106:107], v[52:53] op_sel_hi:[1,0]
	v_pk_mul_f32 v[56:57], v[60:61], v[52:53] op_sel_hi:[1,0]
	v_pk_fma_f32 v[54:55], v[54:55], v[78:79], v[10:11]
	v_pk_fma_f32 v[56:57], v[56:57], v[76:77], v[12:13]
	v_cvt_pk_bf16_f32 v54, v54, v55
	v_pk_fma_f32 v[50:51], v[50:51], v[68:69], v[4:5]
	v_cvt_pk_bf16_f32 v55, v56, v57
	ds_write_b64 v91, v[54:55] offset:32
	v_pk_mul_f32 v[54:55], v[102:103], v[52:53] op_sel_hi:[1,0]
	v_pk_mul_f32 v[56:57], v[58:59], v[52:53] op_sel_hi:[1,0]
	v_pk_fma_f32 v[54:55], v[54:55], v[74:75], v[6:7]
	v_pk_fma_f32 v[56:57], v[56:57], v[72:73], v[8:9]
	v_cvt_pk_bf16_f32 v54, v54, v55
	v_add_u32_e32 v58, 0x50000, v92
	v_cvt_pk_bf16_f32 v55, v56, v57
	ds_write_b64 v91, v[54:55] offset:64
	v_pk_mul_f32 v[54:55], v[98:99], v[52:53] op_sel_hi:[1,0]
	s_nop 0
	v_pk_fma_f32 v[52:53], v[54:55], v[70:71], v[2:3]
	s_nop 0
	v_cvt_pk_bf16_f32 v52, v52, v53
	v_cvt_pk_bf16_f32 v53, v50, v51
	ds_write_b64 v91, v[52:53] offset:96
	ds_read_b128 v[50:53], v90
	ds_read_b128 v[54:57], v90 offset:1152
	s_waitcnt lgkmcnt(1)
	global_store_dwordx4 v84, v[50:53], s[18:19] nt
	s_bitset1_b32 s98, 22
	s_waitcnt lgkmcnt(0)
	global_store_dwordx4 v86, v[54:57], s[18:19] nt
	s_bitset1_b32 s98, 23
	v_cvt_pk_bf16_f32 v50, v44, v45
	v_cvt_pk_bf16_f32 v51, v36, v37
	ds_write_b64 v91, v[50:51]
	v_cvt_pk_bf16_f32 v50, v42, v43
	v_cvt_pk_bf16_f32 v51, v34, v35
	ds_write_b64 v91, v[50:51] offset:32
	v_cvt_pk_bf16_f32 v50, v46, v47
	v_cvt_pk_bf16_f32 v51, v38, v39
	ds_write_b64 v91, v[50:51] offset:64
	v_cvt_pk_bf16_f32 v50, v48, v49
	v_cvt_pk_bf16_f32 v51, v40, v41
	ds_write_b64 v91, v[50:51] offset:96
	ds_read_b128 v[50:53], v90
	ds_read_b128 v[54:57], v90 offset:1152
	v_pk_mul_f32 v[44:45], v[44:45], v[66:67] op_sel_hi:[1,0]
	v_pk_mul_f32 v[36:37], v[36:37], v[66:67] op_sel_hi:[1,0]
	v_pk_fma_f32 v[44:45], v[44:45], v[82:83], v[14:15]
	s_waitcnt lgkmcnt(1)
	global_store_dwordx4 v58, v[50:53], s[40:41] nt
	s_bitset1_b32 s98, 24
	v_pk_fma_f32 v[36:37], v[36:37], v[80:81], v[16:17]
	v_pk_mul_f32 v[34:35], v[34:35], v[66:67] op_sel_hi:[1,0]
	v_add_u32_e32 v50, 0x54000, v92
	s_waitcnt lgkmcnt(0)
	global_store_dwordx4 v50, v[54:57], s[40:41] nt
	s_bitset1_b32 s98, 25
	v_cvt_pk_bf16_f32 v44, v44, v45
	v_cvt_pk_bf16_f32 v45, v36, v37
	v_pk_mul_f32 v[36:37], v[42:43], v[66:67] op_sel_hi:[1,0]
	v_pk_fma_f32 v[34:35], v[34:35], v[76:77], v[12:13]
	v_pk_fma_f32 v[36:37], v[36:37], v[78:79], v[10:11]
	ds_write_b64 v91, v[44:45]
	v_cvt_pk_bf16_f32 v36, v36, v37
	v_cvt_pk_bf16_f32 v37, v34, v35
	v_pk_mul_f32 v[34:35], v[46:47], v[66:67] op_sel_hi:[1,0]
	ds_write_b64 v91, v[36:37] offset:32
	v_pk_mul_f32 v[36:37], v[38:39], v[66:67] op_sel_hi:[1,0]
	v_pk_fma_f32 v[34:35], v[34:35], v[74:75], v[6:7]
	v_pk_fma_f32 v[36:37], v[36:37], v[72:73], v[8:9]
	v_cvt_pk_bf16_f32 v34, v34, v35
	v_add_u32_e32 v42, 0x58000, v92
	v_cvt_pk_bf16_f32 v35, v36, v37
	ds_write_b64 v91, v[34:35] offset:64
	v_pk_mul_f32 v[34:35], v[48:49], v[66:67] op_sel_hi:[1,0]
	v_pk_mul_f32 v[36:37], v[40:41], v[66:67] op_sel_hi:[1,0]
	v_pk_fma_f32 v[34:35], v[34:35], v[70:71], v[2:3]
	v_pk_fma_f32 v[36:37], v[36:37], v[68:69], v[4:5]
	v_cvt_pk_bf16_f32 v34, v34, v35
	s_nop 0
	v_cvt_pk_bf16_f32 v35, v36, v37
	ds_write_b64 v91, v[34:35] offset:96
	ds_read_b128 v[34:37], v90
	ds_read_b128 v[38:41], v90 offset:1152
	s_waitcnt lgkmcnt(1)
	global_store_dwordx4 v58, v[34:37], s[18:19] nt
	s_bitset1_b32 s98, 26
	s_waitcnt lgkmcnt(0)
	global_store_dwordx4 v50, v[38:41], s[18:19] nt
	s_bitset1_b32 s98, 27
	v_cvt_pk_bf16_f32 v34, v32, v33
	v_cvt_pk_bf16_f32 v35, v24, v25
	ds_write_b64 v91, v[34:35]
	v_cvt_pk_bf16_f32 v34, v30, v31
	v_cvt_pk_bf16_f32 v35, v22, v23
	ds_write_b64 v91, v[34:35] offset:32
	v_cvt_pk_bf16_f32 v34, v28, v29
	v_cvt_pk_bf16_f32 v35, v20, v21
	ds_write_b64 v91, v[34:35] offset:64
	v_cvt_pk_bf16_f32 v34, v26, v27
	v_cvt_pk_bf16_f32 v35, v18, v19
	ds_write_b64 v91, v[34:35] offset:96
	ds_read_b128 v[34:37], v90
	ds_read_b128 v[38:41], v90 offset:1152
	s_waitcnt lgkmcnt(1)
	global_store_dwordx4 v42, v[34:37], s[40:41] nt
	s_bitset1_b32 s98, 28
	s_nop 1
	v_add_u32_e32 v35, 0x5c000, v92
	v_mov_b32_e32 v34, v67
	v_pk_mul_f32 v[32:33], v[32:33], v[34:35] op_sel_hi:[1,0]
	s_waitcnt lgkmcnt(0)
	global_store_dwordx4 v35, v[38:41], s[40:41] nt
	s_bitset1_b32 s98, 29
	v_pk_mul_f32 v[24:25], v[24:25], v[34:35] op_sel_hi:[1,0]
	v_pk_fma_f32 v[14:15], v[32:33], v[82:83], v[14:15]
	v_pk_fma_f32 v[16:17], v[24:25], v[80:81], v[16:17]
	v_cvt_pk_bf16_f32 v14, v14, v15
	s_nop 0
	v_cvt_pk_bf16_f32 v15, v16, v17
	ds_write_b64 v91, v[14:15]
	v_pk_mul_f32 v[14:15], v[30:31], v[34:35] op_sel_hi:[1,0]
	v_pk_mul_f32 v[16:17], v[22:23], v[34:35] op_sel_hi:[1,0]
	v_pk_fma_f32 v[10:11], v[14:15], v[78:79], v[10:11]
	v_pk_fma_f32 v[12:13], v[16:17], v[76:77], v[12:13]
	v_cvt_pk_bf16_f32 v10, v10, v11
	s_nop 0
	v_cvt_pk_bf16_f32 v11, v12, v13
	ds_write_b64 v91, v[10:11] offset:32
	v_pk_mul_f32 v[10:11], v[28:29], v[34:35] op_sel_hi:[1,0]
	v_pk_mul_f32 v[12:13], v[20:21], v[34:35] op_sel_hi:[1,0]
	v_pk_fma_f32 v[6:7], v[10:11], v[74:75], v[6:7]
	v_pk_fma_f32 v[8:9], v[12:13], v[72:73], v[8:9]
	v_cvt_pk_bf16_f32 v6, v6, v7
	s_nop 0
	v_cvt_pk_bf16_f32 v7, v8, v9
	ds_write_b64 v91, v[6:7] offset:64
	v_pk_mul_f32 v[6:7], v[26:27], v[34:35] op_sel_hi:[1,0]
	v_pk_mul_f32 v[8:9], v[18:19], v[34:35] op_sel_hi:[1,0]
	v_pk_fma_f32 v[2:3], v[6:7], v[70:71], v[2:3]
	v_pk_fma_f32 v[4:5], v[8:9], v[68:69], v[4:5]
	v_cvt_pk_bf16_f32 v2, v2, v3
	s_nop 0
	v_cvt_pk_bf16_f32 v3, v4, v5
	ds_write_b64 v91, v[2:3] offset:96
	ds_read_b128 v[2:5], v90
	ds_read_b128 v[6:9], v90 offset:1152
	s_waitcnt lgkmcnt(1)
	global_store_dwordx4 v42, v[2:5], s[18:19] nt
	s_bitset1_b32 s98, 30
	s_waitcnt lgkmcnt(0)
	global_store_dwordx4 v35, v[6:9], s[18:19] nt
	s_bitset1_b32 s98, 31
	s_cbranch_vccnz .LBB0_654
	s_andn2_b64 vcc, exec, s[46:47]
	s_cbranch_vccnz .LBB0_653
	s_barrier
	s_branch .LBB0_653
.Lrwp4_first:
	ds_read_b128 v[130:133], v231
	ds_read_b128 v[134:137], v231 offset:1024
	ds_read_b128 v[138:141], v231 offset:2048
	ds_read_b128 v[142:145], v231 offset:3072
	ds_read_b128 v[146:149], v232
	ds_read_b128 v[150:153], v232 offset:1024
	ds_read_b128 v[154:157], v232 offset:2048
	ds_read_b128 v[158:161], v232 offset:3072
	s_add_u32 s6, s0, 0xfffc0080
	s_addc_u32 s7, s1, -1
	s_cmp_eq_u32 s67, 12
	s_cselect_b32 s11, s31, s7
	s_cselect_b32 s10, s57, s6
	s_cselect_b32 s9, s55, s66
	s_cselect_b32 s8, s63, s65
	v_lshl_add_u64 v[208:209], s[0:1], 0, v[198:199]
	s_add_i32 m0, s77, 0xc000
	ds_read_b128 v[162:165], v233
	ds_read_b128 v[166:169], v233 offset:1024
	ds_read_b128 v[170:173], v233 offset:2048
	ds_read_b128 v[174:177], v233 offset:3072
	ds_read_b128 v[178:181], v233 offset:4096
	ds_read_b128 v[182:185], v233 offset:5120
	ds_read_b128 v[186:189], v233 offset:6144
	ds_read_b128 v[190:193], v233 offset:7168
	global_load_lds_dwordx4 v[208:209], off
	v_lshl_add_u64 v[208:209], s[0:1], 0, v[200:201]
	s_add_i32 m0, s77, 0xe000
	s_nop 0
	global_load_lds_dwordx4 v[208:209], off
	s_cmp_eq_u32 s98, -1
	s_cbranch_scc1 .Lrwp4_a32
	s_waitcnt vmcnt(8)
	s_branch .Lrwp4_adone

.Lrwp4_adone:
	s_waitcnt lgkmcnt(0)
	s_barrier
	s_setprio 1
	s_waitcnt lgkmcnt(0)
	v_mfma_f32_16x16x32_bf16 v[126:129], v[130:133], v[162:165], v[126:129]
	v_mfma_f32_16x16x32_bf16 v[122:125], v[138:141], v[162:165], v[122:125]
	v_mfma_f32_16x16x32_bf16 v[110:113], v[130:133], v[170:173], v[110:113]
	v_mfma_f32_16x16x32_bf16 v[106:109], v[138:141], v[170:173], v[106:109]
	v_mfma_f32_16x16x32_bf16 v[94:97], v[130:133], v[178:181], v[94:97]
	v_mfma_f32_16x16x32_bf16 v[90:93], v[138:141], v[178:181], v[90:93]
	v_mfma_f32_16x16x32_bf16 v[78:81], v[130:133], v[186:189], v[78:81]
	v_mfma_f32_16x16x32_bf16 v[74:77], v[138:141], v[186:189], v[74:77]
	v_mfma_f32_16x16x32_bf16 v[126:129], v[134:137], v[166:169], v[126:129]
	v_mfma_f32_16x16x32_bf16 v[122:125], v[142:145], v[166:169], v[122:125]
	v_mfma_f32_16x16x32_bf16 v[110:113], v[134:137], v[174:177], v[110:113]
	v_mfma_f32_16x16x32_bf16 v[106:109], v[142:145], v[174:177], v[106:109]
	v_mfma_f32_16x16x32_bf16 v[94:97], v[134:137], v[182:185], v[94:97]
	v_mfma_f32_16x16x32_bf16 v[90:93], v[142:145], v[182:185], v[90:93]
	v_mfma_f32_16x16x32_bf16 v[78:81], v[134:137], v[190:193], v[78:81]
	v_mfma_f32_16x16x32_bf16 v[74:77], v[142:145], v[190:193], v[74:77]
	s_setprio 0
	s_setprio 1
	v_mfma_f32_16x16x32_bf16 v[118:121], v[146:149], v[162:165], v[118:121]
	v_mfma_f32_16x16x32_bf16 v[114:117], v[154:157], v[162:165], v[114:117]
	v_mfma_f32_16x16x32_bf16 v[102:105], v[146:149], v[170:173], v[102:105]
	v_mfma_f32_16x16x32_bf16 v[98:101], v[154:157], v[170:173], v[98:101]
	v_mfma_f32_16x16x32_bf16 v[86:89], v[146:149], v[178:181], v[86:89]
	v_mfma_f32_16x16x32_bf16 v[82:85], v[154:157], v[178:181], v[82:85]
	v_mfma_f32_16x16x32_bf16 v[70:73], v[146:149], v[186:189], v[70:73]
	v_mfma_f32_16x16x32_bf16 v[66:69], v[154:157], v[186:189], v[66:69]
	v_mfma_f32_16x16x32_bf16 v[118:121], v[150:153], v[166:169], v[118:121]
	v_mfma_f32_16x16x32_bf16 v[114:117], v[158:161], v[166:169], v[114:117]
	v_mfma_f32_16x16x32_bf16 v[102:105], v[150:153], v[174:177], v[102:105]
	v_mfma_f32_16x16x32_bf16 v[98:101], v[158:161], v[174:177], v[98:101]
	v_mfma_f32_16x16x32_bf16 v[86:89], v[150:153], v[182:185], v[86:89]
	v_mfma_f32_16x16x32_bf16 v[82:85], v[158:161], v[182:185], v[82:85]
	v_mfma_f32_16x16x32_bf16 v[70:73], v[150:153], v[190:193], v[70:73]
	v_mfma_f32_16x16x32_bf16 v[66:69], v[158:161], v[190:193], v[66:69]
	s_setprio 0
	s_barrier
	s_add_i32 s6, s94, s76
	v_lshl_add_u64 v[208:209], s[8:9], 0, v[194:195]
	s_mov_b32 m0, s6
	ds_read_b128 v[162:165], v233 offset:16384
	ds_read_b128 v[166:169], v233 offset:17408
	ds_read_b128 v[170:173], v233 offset:18432
	ds_read_b128 v[174:177], v233 offset:19456
	ds_read_b128 v[178:181], v233 offset:20480
	ds_read_b128 v[182:185], v233 offset:21504
	ds_read_b128 v[186:189], v233 offset:22528
	ds_read_b128 v[190:193], v233 offset:23552
	global_load_lds_dwordx4 v[208:209], off
	s_add_i32 m0, s6, 0x2000
	s_add_u32 s6, s8, 0x40000
	v_lshl_add_u64 v[210:211], s[8:9], 0, v[196:197]
	s_addc_u32 s7, s9, 0
	s_add_i32 s70, s95, s76
	global_load_lds_dwordx4 v[210:211], off
	v_lshl_add_u64 v[212:213], s[6:7], 0, v[194:195]
	s_mov_b32 m0, s70
	v_lshl_add_u64 v[214:215], s[10:11], 0, v[196:197]
	global_load_lds_dwordx4 v[212:213], off
	v_lshl_add_u64 v[212:213], s[6:7], 0, v[196:197]
	s_add_i32 m0, s70, 0x2000
	s_nop 0
	global_load_lds_dwordx4 v[212:213], off
	v_lshl_add_u64 v[212:213], s[10:11], 0, v[194:195]
	s_mov_b32 m0, s77
	s_nop 0
	global_load_lds_dwordx4 v[212:213], off
	s_mov_b32 m0, s78
	s_nop 0
	global_load_lds_dwordx4 v[214:215], off
	s_cmp_eq_u32 s98, -1
	s_cbranch_scc1 .Lrwp4_b32
	s_waitcnt vmcnt(8)
	s_branch .Lrwp4_bdone

.Lrwp4_bdone:
	s_mov_b32 s98, 0
	s_waitcnt lgkmcnt(0)
	s_barrier
	s_setprio 1
	s_waitcnt lgkmcnt(0)
	v_mfma_f32_16x16x32_bf16 v[58:61], v[130:133], v[162:165], v[58:61]
	v_mfma_f32_16x16x32_bf16 v[62:65], v[138:141], v[162:165], v[62:65]
	v_mfma_f32_16x16x32_bf16 v[46:49], v[130:133], v[170:173], v[46:49]
	v_mfma_f32_16x16x32_bf16 v[42:45], v[138:141], v[170:173], v[42:45]
	v_mfma_f32_16x16x32_bf16 v[30:33], v[130:133], v[178:181], v[30:33]
	v_mfma_f32_16x16x32_bf16 v[26:29], v[138:141], v[178:181], v[26:29]
	v_mfma_f32_16x16x32_bf16 v[14:17], v[130:133], v[186:189], v[14:17]
	v_mfma_f32_16x16x32_bf16 v[10:13], v[138:141], v[186:189], v[10:13]
	v_mfma_f32_16x16x32_bf16 v[58:61], v[134:137], v[166:169], v[58:61]
	v_mfma_f32_16x16x32_bf16 v[62:65], v[142:145], v[166:169], v[62:65]
	v_mfma_f32_16x16x32_bf16 v[46:49], v[134:137], v[174:177], v[46:49]
	v_mfma_f32_16x16x32_bf16 v[42:45], v[142:145], v[174:177], v[42:45]
	v_mfma_f32_16x16x32_bf16 v[30:33], v[134:137], v[182:185], v[30:33]
	v_mfma_f32_16x16x32_bf16 v[26:29], v[142:145], v[182:185], v[26:29]
	v_mfma_f32_16x16x32_bf16 v[14:17], v[134:137], v[190:193], v[14:17]
	v_mfma_f32_16x16x32_bf16 v[10:13], v[142:145], v[190:193], v[10:13]
	s_setprio 0
	s_setprio 1
	v_mfma_f32_16x16x32_bf16 v[54:57], v[146:149], v[162:165], v[54:57]
	v_mfma_f32_16x16x32_bf16 v[50:53], v[154:157], v[162:165], v[50:53]
	v_mfma_f32_16x16x32_bf16 v[38:41], v[146:149], v[170:173], v[38:41]
	v_mfma_f32_16x16x32_bf16 v[34:37], v[154:157], v[170:173], v[34:37]
	v_mfma_f32_16x16x32_bf16 v[22:25], v[146:149], v[178:181], v[22:25]
	v_mfma_f32_16x16x32_bf16 v[18:21], v[154:157], v[178:181], v[18:21]
	v_mfma_f32_16x16x32_bf16 v[6:9], v[146:149], v[186:189], v[6:9]
	v_mfma_f32_16x16x32_bf16 v[2:5], v[154:157], v[186:189], v[2:5]
	v_mfma_f32_16x16x32_bf16 v[54:57], v[150:153], v[166:169], v[54:57]
	v_mfma_f32_16x16x32_bf16 v[50:53], v[158:161], v[166:169], v[50:53]
	v_mfma_f32_16x16x32_bf16 v[38:41], v[150:153], v[174:177], v[38:41]
	v_mfma_f32_16x16x32_bf16 v[34:37], v[158:161], v[174:177], v[34:37]
	v_mfma_f32_16x16x32_bf16 v[22:25], v[150:153], v[182:185], v[22:25]
	v_mfma_f32_16x16x32_bf16 v[18:21], v[158:161], v[182:185], v[18:21]
	v_mfma_f32_16x16x32_bf16 v[6:9], v[150:153], v[190:193], v[6:9]
	v_mfma_f32_16x16x32_bf16 v[2:5], v[158:161], v[190:193], v[2:5]
	s_setprio 0
	s_barrier
	s_add_i32 s70, 0, 0x18000
	s_add_i32 s71, 0, 0x1c000
	v_add_u32_e32 v142, s70, v230
	v_add_u32_e32 v158, s71, v230
	ds_read_b128 v[130:133], v142
	ds_read_b128 v[134:137], v142 offset:1024
	ds_read_b128 v[138:141], v142 offset:2048
	ds_read_b128 v[142:145], v142 offset:3072
	ds_read_b128 v[146:149], v158
	ds_read_b128 v[150:153], v158 offset:1024
	ds_read_b128 v[154:157], v158 offset:2048
	ds_read_b128 v[158:161], v158 offset:3072
	s_add_u32 s6, s10, 0x40000
	s_addc_u32 s7, s11, 0
	s_mov_b32 m0, s79
	v_lshl_add_u64 v[216:217], s[6:7], 0, v[194:195]
	ds_read_b128 v[162:165], v233 offset:32768
	ds_read_b128 v[166:169], v233 offset:33792
	ds_read_b128 v[170:173], v233 offset:34816
	ds_read_b128 v[174:177], v233 offset:35840
	ds_read_b128 v[178:181], v233 offset:36864
	ds_read_b128 v[182:185], v233 offset:37888
	ds_read_b128 v[186:189], v233 offset:38912
	ds_read_b128 v[190:193], v233 offset:39936
	global_load_lds_dwordx4 v[216:217], off
	v_lshl_add_u64 v[216:217], s[6:7], 0, v[196:197]
	s_mov_b32 m0, s80
	s_nop 0
	global_load_lds_dwordx4 v[216:217], off
	s_waitcnt vmcnt(8)
	s_waitcnt lgkmcnt(0)
	s_barrier
	s_setprio 1
	s_waitcnt lgkmcnt(0)
	v_mfma_f32_16x16x32_bf16 v[126:129], v[130:133], v[162:165], v[126:129]
	v_mfma_f32_16x16x32_bf16 v[122:125], v[138:141], v[162:165], v[122:125]
	v_mfma_f32_16x16x32_bf16 v[110:113], v[130:133], v[170:173], v[110:113]
	v_mfma_f32_16x16x32_bf16 v[106:109], v[138:141], v[170:173], v[106:109]
	v_mfma_f32_16x16x32_bf16 v[94:97], v[130:133], v[178:181], v[94:97]
	v_mfma_f32_16x16x32_bf16 v[90:93], v[138:141], v[178:181], v[90:93]
	v_mfma_f32_16x16x32_bf16 v[78:81], v[130:133], v[186:189], v[78:81]
	v_mfma_f32_16x16x32_bf16 v[74:77], v[138:141], v[186:189], v[74:77]
	v_mfma_f32_16x16x32_bf16 v[126:129], v[134:137], v[166:169], v[126:129]
	v_mfma_f32_16x16x32_bf16 v[122:125], v[142:145], v[166:169], v[122:125]
	v_mfma_f32_16x16x32_bf16 v[110:113], v[134:137], v[174:177], v[110:113]
	v_mfma_f32_16x16x32_bf16 v[106:109], v[142:145], v[174:177], v[106:109]
	v_mfma_f32_16x16x32_bf16 v[94:97], v[134:137], v[182:185], v[94:97]
	v_mfma_f32_16x16x32_bf16 v[90:93], v[142:145], v[182:185], v[90:93]
	v_mfma_f32_16x16x32_bf16 v[78:81], v[134:137], v[190:193], v[78:81]
	v_mfma_f32_16x16x32_bf16 v[74:77], v[142:145], v[190:193], v[74:77]
	s_setprio 0
	s_setprio 1
	v_mfma_f32_16x16x32_bf16 v[118:121], v[146:149], v[162:165], v[118:121]
	v_mfma_f32_16x16x32_bf16 v[114:117], v[154:157], v[162:165], v[114:117]
	v_mfma_f32_16x16x32_bf16 v[102:105], v[146:149], v[170:173], v[102:105]
	v_mfma_f32_16x16x32_bf16 v[98:101], v[154:157], v[170:173], v[98:101]
	v_mfma_f32_16x16x32_bf16 v[86:89], v[146:149], v[178:181], v[86:89]
	v_mfma_f32_16x16x32_bf16 v[82:85], v[154:157], v[178:181], v[82:85]
	v_mfma_f32_16x16x32_bf16 v[70:73], v[146:149], v[186:189], v[70:73]
	v_mfma_f32_16x16x32_bf16 v[66:69], v[154:157], v[186:189], v[66:69]
	v_mfma_f32_16x16x32_bf16 v[118:121], v[150:153], v[166:169], v[118:121]
	v_mfma_f32_16x16x32_bf16 v[114:117], v[158:161], v[166:169], v[114:117]
	v_mfma_f32_16x16x32_bf16 v[102:105], v[150:153], v[174:177], v[102:105]
	v_mfma_f32_16x16x32_bf16 v[98:101], v[158:161], v[174:177], v[98:101]
	v_mfma_f32_16x16x32_bf16 v[86:89], v[150:153], v[182:185], v[86:89]
	v_mfma_f32_16x16x32_bf16 v[82:85], v[158:161], v[182:185], v[82:85]
	v_mfma_f32_16x16x32_bf16 v[70:73], v[150:153], v[190:193], v[70:73]
	v_mfma_f32_16x16x32_bf16 v[66:69], v[158:161], v[190:193], v[66:69]
	s_setprio 0
	s_barrier
	s_add_i32 s6, s70, s76
	v_lshl_add_u64 v[208:209], v[208:209], 0, s[50:51]
	s_mov_b32 m0, s6
	ds_read_b128 v[162:165], v233 offset:49152
	ds_read_b128 v[166:169], v233 offset:50176
	ds_read_b128 v[170:173], v233 offset:51200
	ds_read_b128 v[174:177], v233 offset:52224
	ds_read_b128 v[178:181], v233 offset:53248
	ds_read_b128 v[182:185], v233 offset:54272
	ds_read_b128 v[186:189], v233 offset:55296
	ds_read_b128 v[190:193], v233 offset:56320
	global_load_lds_dwordx4 v[208:209], off
	s_add_i32 m0, s6, 0x2000
	s_add_u32 s6, s8, 0x40080
	v_lshl_add_u64 v[208:209], v[210:211], 0, s[50:51]
	s_addc_u32 s7, s9, 0
	s_add_i32 s8, s71, s76
	global_load_lds_dwordx4 v[208:209], off
	v_lshl_add_u64 v[208:209], s[6:7], 0, v[194:195]
	s_mov_b32 m0, s8
	s_nop 0
	global_load_lds_dwordx4 v[208:209], off
	v_lshl_add_u64 v[208:209], s[6:7], 0, v[196:197]
	s_add_i32 m0, s8, 0x2000
	s_nop 0
	global_load_lds_dwordx4 v[208:209], off
	v_lshl_add_u64 v[208:209], v[212:213], 0, s[50:51]
	s_mov_b32 m0, s86
	s_nop 0
	global_load_lds_dwordx4 v[208:209], off
	v_lshl_add_u64 v[208:209], v[214:215], 0, s[50:51]
	s_mov_b32 m0, s87
	s_nop 0
	global_load_lds_dwordx4 v[208:209], off
	s_waitcnt vmcnt(8)
	s_waitcnt lgkmcnt(0)
	s_barrier
	s_setprio 1
	s_waitcnt lgkmcnt(0)
	v_mfma_f32_16x16x32_bf16 v[58:61], v[130:133], v[162:165], v[58:61]
	v_mfma_f32_16x16x32_bf16 v[62:65], v[138:141], v[162:165], v[62:65]
	v_mfma_f32_16x16x32_bf16 v[46:49], v[130:133], v[170:173], v[46:49]
	v_mfma_f32_16x16x32_bf16 v[42:45], v[138:141], v[170:173], v[42:45]
	v_mfma_f32_16x16x32_bf16 v[30:33], v[130:133], v[178:181], v[30:33]
	v_mfma_f32_16x16x32_bf16 v[26:29], v[138:141], v[178:181], v[26:29]
	v_mfma_f32_16x16x32_bf16 v[14:17], v[130:133], v[186:189], v[14:17]
	v_mfma_f32_16x16x32_bf16 v[10:13], v[138:141], v[186:189], v[10:13]
	v_mfma_f32_16x16x32_bf16 v[58:61], v[134:137], v[166:169], v[58:61]
	v_mfma_f32_16x16x32_bf16 v[62:65], v[142:145], v[166:169], v[62:65]
	v_mfma_f32_16x16x32_bf16 v[46:49], v[134:137], v[174:177], v[46:49]
	v_mfma_f32_16x16x32_bf16 v[42:45], v[142:145], v[174:177], v[42:45]
	v_mfma_f32_16x16x32_bf16 v[30:33], v[134:137], v[182:185], v[30:33]
	v_mfma_f32_16x16x32_bf16 v[26:29], v[142:145], v[182:185], v[26:29]
	v_mfma_f32_16x16x32_bf16 v[14:17], v[134:137], v[190:193], v[14:17]
	v_mfma_f32_16x16x32_bf16 v[10:13], v[142:145], v[190:193], v[10:13]
	s_setprio 0
	s_setprio 1
	v_mfma_f32_16x16x32_bf16 v[54:57], v[146:149], v[162:165], v[54:57]
	v_mfma_f32_16x16x32_bf16 v[50:53], v[154:157], v[162:165], v[50:53]
	v_mfma_f32_16x16x32_bf16 v[38:41], v[146:149], v[170:173], v[38:41]
	v_mfma_f32_16x16x32_bf16 v[34:37], v[154:157], v[170:173], v[34:37]
	v_mfma_f32_16x16x32_bf16 v[22:25], v[146:149], v[178:181], v[22:25]
	v_mfma_f32_16x16x32_bf16 v[18:21], v[154:157], v[178:181], v[18:21]
	v_mfma_f32_16x16x32_bf16 v[6:9], v[146:149], v[186:189], v[6:9]
	v_mfma_f32_16x16x32_bf16 v[2:5], v[154:157], v[186:189], v[2:5]
	v_mfma_f32_16x16x32_bf16 v[54:57], v[150:153], v[166:169], v[54:57]
	v_mfma_f32_16x16x32_bf16 v[50:53], v[158:161], v[166:169], v[50:53]
	v_mfma_f32_16x16x32_bf16 v[38:41], v[150:153], v[174:177], v[38:41]
	v_mfma_f32_16x16x32_bf16 v[34:37], v[158:161], v[174:177], v[34:37]
	v_mfma_f32_16x16x32_bf16 v[22:25], v[150:153], v[182:185], v[22:25]
	v_mfma_f32_16x16x32_bf16 v[18:21], v[158:161], v[182:185], v[18:21]
	v_mfma_f32_16x16x32_bf16 v[6:9], v[150:153], v[190:193], v[6:9]
	v_mfma_f32_16x16x32_bf16 v[2:5], v[158:161], v[190:193], v[2:5]
	s_setprio 0
	s_barrier
	s_add_i32 s67, s67, 2
	s_add_u32 s0, s0, 0x100
	s_addc_u32 s1, s1, 0
	s_add_u32 s65, s65, 0x100
	s_addc_u32 s66, s66, 0
	s_cmp_gt_u32 s67, 13
	s_cbranch_scc0 .LBB0_662
	s_branch .Lrwp4_exit
.Lrwp4_prelaxed:
	s_waitcnt vmcnt(32)
	s_branch .Lrwp4_pdone

.LBB0_845:
	s_add_u32 s69, s26, 0x105000
	s_addc_u32 s70, s27, 0
	s_add_u32 s16, s26, 0x2300000
	s_addc_u32 s17, s27, 0
	s_add_u32 s71, s26, 0x20000
	s_mov_b64 s[18:19], 0x80
	s_addc_u32 s72, s27, 0
	s_and_b32 s1, s1, 3
	s_add_i32 m0, s64, 0x18000
	v_lshl_add_u64 v[8:9], v[8:9], 0, s[18:19]
	s_lshl_b32 s73, s0, 6
	s_lshl_b32 s7, s0, 13
	s_lshl_b32 s74, s1, 5
	s_lshl_b32 s30, s1, 12
	s_waitcnt vmcnt(2)
	s_barrier
	global_load_lds_dwordx4 v[8:9], off
	v_lshl_add_u64 v[6:7], v[6:7], 0, s[18:19]
	s_add_i32 m0, s64, 0x1a000
	s_add_i32 s75, s64, 0x8000
	s_add_i32 s76, s64, 0xa000
	global_load_lds_dwordx4 v[6:7], off
	v_lshl_add_u64 v[4:5], v[4:5], 0, s[18:19]
	s_mov_b32 m0, s75
	s_add_u32 s26, s8, 0x100080
	global_load_lds_dwordx4 v[4:5], off
	v_lshl_add_u64 v[2:3], v[2:3], 0, s[18:19]
	s_mov_b32 m0, s76
	s_addc_u32 s27, s9, 0
	global_load_lds_dwordx4 v[2:3], off
	s_add_i32 m0, s64, 0x1c000
	v_lshl_add_u64 v[2:3], s[26:27], 0, v[146:147]
	global_load_lds_dwordx4 v[2:3], off
	v_lshl_add_u64 v[2:3], s[26:27], 0, v[148:149]
	s_add_i32 m0, s64, 0x1e000
	v_bfe_u32 v191, v10, 4, 2
	global_load_lds_dwordx4 v[2:3], off
	v_and_b32_e32 v190, 15, v10
	v_lshlrev_b32_e32 v2, 4, v191
	v_lshlrev_b32_e32 v3, 2, v10
	v_lshl_or_b32 v2, v190, 6, v2
	v_and_b32_e32 v3, 32, v3
	v_bitop3_b32 v4, v2, s7, v3 bitop3:0xde
	v_bitop3_b32 v192, v2, s30, v3 bitop3:0xde
	v_lshlrev_b32_e32 v2, 16, v11
	v_and_b32_e32 v2, 0xfffe0000, v2
	v_lshl_add_u32 v2, v12, 13, v2
	v_and_b32_e32 v3, 1, v11
	v_lshl_or_b32 v2, v3, 6, v2
	v_lshl_add_u32 v150, v13, 1, v2
	v_lshlrev_b32_e32 v2, 16, v14
	s_cmpk_lt_u32 s10, 0x100
	v_and_b32_e32 v2, 0xfffe0000, v2
	s_waitcnt vmcnt(6)
	s_cselect_b64 s[26:27], -1, 0
	s_lshl_b32 s1, s1, 2
	s_lshl_b32 s0, s0, 8
	v_lshl_add_u32 v2, v15, 13, v2
	v_and_b32_e32 v3, 1, v14
	s_add_i32 s81, s1, 0
	s_add_i32 s82, s0, 0
	v_lshl_or_b32 v2, v3, 6, v2
	s_add_i32 s84, 0, 0x10000
	s_add_i32 s85, 0, 0x14000
	s_mov_b32 s77, 0x18000
	s_mov_b32 s78, 0x8000
	s_ashr_i32 s79, s3, 31
	s_ashr_i32 s80, s2, 31
	s_add_i32 s81, s81, 0x20000
	s_add_i32 s82, s82, 0x21000
	v_mov_b32_e32 v151, v147
	v_lshl_add_u32 v152, v16, 1, v2
	v_mov_b32_e32 v153, v147
	v_mov_b64_e32 v[154:155], 0x400
	v_mov_b64_e32 v[156:157], 0x3ff
	s_movk_i32 s83, 0xffe0
	v_add_u32_e32 v193, s84, v192
	v_add_u32_e32 v194, s85, v192
	v_add_u32_e32 v195, 0, v4
	s_mov_b64 s[30:31], 0x8000
	s_mov_b64 s[34:35], 0x10000
	s_mov_b64 s[36:37], 0x18000
	s_mov_b64 s[38:39], 0x40000
	s_mov_b64 s[42:43], 0x48000
	s_mov_b32 s86, 0x48000
	s_mov_b64 s[44:45], 0x50000
	s_mov_b32 s87, 0x50000
	s_mov_b64 s[46:47], 0x58000
	s_mov_b32 s88, 0x58000
	s_add_i32 s89, 0, 0x21400
	v_mov_b32_e32 v196, 0x358637bd
	s_mov_b32 s90, 0xf800000
	v_mov_b32_e32 v197, 0x260
	v_mov_b64_e32 v[158:159], 0x1e8481
	s_mov_b32 s98, 0
	s_mov_b32 s91, 0
	s_barrier
	s_branch .LBB0_848

.LBB0_854:
	s_ashr_i32 s51, s50, 31
	s_lshl_b64 s[52:53], s[50:51], 21
	s_add_u32 s52, s14, s52
	s_addc_u32 s53, s15, s53
	s_and_b64 s[54:55], s[0:1], exec
	s_cselect_b32 s7, s53, s5
	s_cselect_b32 s10, s52, s4
	s_ashr_i32 s49, s48, 31
	s_lshl_b64 s[54:55], s[48:49], 21
	s_add_u32 s54, s28, s54
	s_addc_u32 s55, s29, s55
	s_and_b64 s[58:59], s[0:1], exec
	s_cselect_b32 s49, s55, s9
	s_cselect_b32 s51, s54, s8
	s_add_u32 s4, s4, 0x100080
	s_addc_u32 s5, s5, 0
	s_add_u32 s57, s8, 0x100
	v_mov_b32_e32 v2, 0
	s_addc_u32 s60, s9, 0
	s_mov_b32 s61, -2
	v_mov_b32_e32 v3, v2
	v_mov_b32_e32 v4, v2
	v_mov_b32_e32 v5, v2
	v_mov_b32_e32 v6, v2
	v_mov_b32_e32 v7, v2
	v_mov_b32_e32 v8, v2
	v_mov_b32_e32 v9, v2
	v_mov_b32_e32 v18, v2
	v_mov_b32_e32 v19, v2
	v_mov_b32_e32 v20, v2
	v_mov_b32_e32 v21, v2
	v_mov_b32_e32 v22, v2
	v_mov_b32_e32 v23, v2
	v_mov_b32_e32 v24, v2
	v_mov_b32_e32 v25, v2
	v_mov_b32_e32 v34, v2
	v_mov_b32_e32 v35, v2
	v_mov_b32_e32 v36, v2
	v_mov_b32_e32 v37, v2
	v_mov_b32_e32 v38, v2
	v_mov_b32_e32 v39, v2
	v_mov_b32_e32 v40, v2
	v_mov_b32_e32 v41, v2
	v_mov_b32_e32 v50, v2
	v_mov_b32_e32 v51, v2
	v_mov_b32_e32 v52, v2
	v_mov_b32_e32 v53, v2
	v_mov_b32_e32 v54, v2
	v_mov_b32_e32 v55, v2
	v_mov_b32_e32 v56, v2
	v_mov_b32_e32 v57, v2
	v_mov_b32_e32 v10, v2
	v_mov_b32_e32 v11, v2
	v_mov_b32_e32 v12, v2
	v_mov_b32_e32 v13, v2
	v_mov_b32_e32 v14, v2
	v_mov_b32_e32 v15, v2
	v_mov_b32_e32 v16, v2
	v_mov_b32_e32 v17, v2
	v_mov_b32_e32 v26, v2
	v_mov_b32_e32 v27, v2
	v_mov_b32_e32 v28, v2
	v_mov_b32_e32 v29, v2
	v_mov_b32_e32 v30, v2
	v_mov_b32_e32 v31, v2
	v_mov_b32_e32 v32, v2
	v_mov_b32_e32 v33, v2
	v_mov_b32_e32 v42, v2
	v_mov_b32_e32 v43, v2
	v_mov_b32_e32 v44, v2
	v_mov_b32_e32 v45, v2
	v_mov_b32_e32 v46, v2
	v_mov_b32_e32 v47, v2
	v_mov_b32_e32 v48, v2
	v_mov_b32_e32 v49, v2
	v_mov_b32_e32 v62, v2
	v_mov_b32_e32 v63, v2
	v_mov_b32_e32 v64, v2
	v_mov_b32_e32 v65, v2
	v_mov_b32_e32 v58, v2
	v_mov_b32_e32 v59, v2
	v_mov_b32_e32 v60, v2
	v_mov_b32_e32 v61, v2
	v_mov_b32_e32 v66, v2
	v_mov_b32_e32 v67, v2
	v_mov_b32_e32 v68, v2
	v_mov_b32_e32 v69, v2
	v_mov_b32_e32 v70, v2
	v_mov_b32_e32 v71, v2
	v_mov_b32_e32 v72, v2
	v_mov_b32_e32 v73, v2
	v_mov_b32_e32 v82, v2
	v_mov_b32_e32 v83, v2
	v_mov_b32_e32 v84, v2
	v_mov_b32_e32 v85, v2
	v_mov_b32_e32 v86, v2
	v_mov_b32_e32 v87, v2
	v_mov_b32_e32 v88, v2
	v_mov_b32_e32 v89, v2
	v_mov_b32_e32 v98, v2
	v_mov_b32_e32 v99, v2
	v_mov_b32_e32 v100, v2
	v_mov_b32_e32 v101, v2
	v_mov_b32_e32 v102, v2
	v_mov_b32_e32 v103, v2
	v_mov_b32_e32 v104, v2
	v_mov_b32_e32 v105, v2
	v_mov_b32_e32 v114, v2
	v_mov_b32_e32 v115, v2
	v_mov_b32_e32 v116, v2
	v_mov_b32_e32 v117, v2
	v_mov_b32_e32 v122, v2
	v_mov_b32_e32 v123, v2
	v_mov_b32_e32 v124, v2
	v_mov_b32_e32 v125, v2
	v_mov_b32_e32 v74, v2
	v_mov_b32_e32 v75, v2
	v_mov_b32_e32 v76, v2
	v_mov_b32_e32 v77, v2
	v_mov_b32_e32 v78, v2
	v_mov_b32_e32 v79, v2
	v_mov_b32_e32 v80, v2
	v_mov_b32_e32 v81, v2
	v_mov_b32_e32 v90, v2
	v_mov_b32_e32 v91, v2
	v_mov_b32_e32 v92, v2
	v_mov_b32_e32 v93, v2
	v_mov_b32_e32 v94, v2
	v_mov_b32_e32 v95, v2
	v_mov_b32_e32 v96, v2
	v_mov_b32_e32 v97, v2
	v_mov_b32_e32 v106, v2
	v_mov_b32_e32 v107, v2
	v_mov_b32_e32 v108, v2
	v_mov_b32_e32 v109, v2
	v_mov_b32_e32 v110, v2
	v_mov_b32_e32 v111, v2
	v_mov_b32_e32 v112, v2
	v_mov_b32_e32 v113, v2
	v_mov_b32_e32 v138, v2
	v_mov_b32_e32 v139, v2
	v_mov_b32_e32 v140, v2
	v_mov_b32_e32 v141, v2
	v_mov_b32_e32 v142, v2
	v_mov_b32_e32 v143, v2
	v_mov_b32_e32 v144, v2
	v_mov_b32_e32 v145, v2
	s_cmp_lg_u32 s98, 0
	s_cbranch_scc1 .Lrwp7_first

.Lrwp7_exit:
	s_and_b64 vcc, exec, s[26:27]
	s_cbranch_vccz .LBB0_858
	s_barrier

.LBB0_900:
	s_or_b64 exec, exec, s[6:7]
	s_or_b32 s4, s51, s74
	s_ashr_i32 s5, s4, 31
	s_lshl_b64 s[6:7], s[4:5], 2
	s_add_u32 s6, s22, s6
	s_waitcnt lgkmcnt(0)
	s_barrier
	v_lshl_add_u32 v2, v199, 2, s82
	v_ashrrev_i32_e32 v161, 31, v160
	s_addc_u32 s7, s23, s7
	ds_read2_b32 v[172:173], v2 offset1:16
	ds_read2_b32 v[126:127], v2 offset0:32 offset1:48
	ds_read2_b32 v[120:121], v2 offset0:128 offset1:144
	ds_read2_b32 v[118:119], v2 offset0:160 offset1:176
	s_waitcnt lgkmcnt(0)
	s_waitcnt vmcnt(2)
	v_lshl_add_u64 v[2:3], v[160:161], 2, s[6:7]
	global_load_dwordx4 v[14:17], v[2:3], off
	global_load_dwordx4 v[10:13], v[2:3], off offset:64
	global_load_dwordx4 v[6:9], v[2:3], off offset:512
	s_nop 0
	global_load_dwordx4 v[2:5], v[2:3], off offset:576
	v_cmp_gt_i32_e32 vcc, 8, v199
	s_waitcnt lgkmcnt(3)
	v_pk_mul_f32 v[136:137], v[142:143], v[172:173] op_sel_hi:[1,0]
	v_pk_mul_f32 v[138:139], v[138:139], v[172:173] op_sel_hi:[1,0]
	v_pk_mul_f32 v[140:141], v[140:141], v[172:173] op_sel_hi:[1,0]
	v_and_or_b32 v128, v199, 7, s49
	v_cndmask_b32_e64 v129, 64, 0, vcc
	v_mov_b32_e32 v178, 0
	v_mov_b32_e32 v179, 0
	v_mov_b32_e32 v181, 0
	v_mov_b32_e32 v183, 0
	v_mov_b32_e32 v185, 0
	v_pk_mul_f32 v[142:143], v[144:145], v[172:173] op_sel_hi:[1,0]
	v_pk_mul_f32 v[122:123], v[122:123], v[172:173] op_sel_hi:[1,0]
	v_pk_mul_f32 v[124:125], v[124:125], v[172:173] op_sel_hi:[1,0]
	v_mov_b32_e32 v180, 0
	v_mov_b32_e32 v182, 0
	v_mov_b32_e32 v184, 0
	v_mov_b32_e32 v186, 0
	v_mov_b32_e32 v188, 0
	v_mov_b32_e32 v199, 0
	v_mov_b32_e32 v201, 0
	v_lshlrev_b32_e32 v128, 12, v128
	v_lshl_add_u32 v129, v198, 4, v129
	s_lshl_b32 s4, s4, 2
	v_pk_mul_f32 v[114:115], v[114:115], v[172:173] op_sel_hi:[1,0]
	v_pk_mul_f32 v[116:117], v[116:117], v[172:173] op_sel_hi:[1,0]
	v_add3_u32 v128, v129, v128, s4
	v_add_u32_e32 v198, 0x8000, v128
	v_mov_b32_e32 v187, 0
	v_mov_b32_e32 v189, 0
	v_mov_b32_e32 v200, 0
	v_mov_b32_e32 v202, 0
	v_add_u32_e32 v129, 0x200, v128
	s_waitcnt lgkmcnt(2)
	v_pk_mul_f32 v[90:91], v[90:91], v[126:127] op_sel_hi:[1,0]
	v_pk_mul_f32 v[92:93], v[92:93], v[126:127] op_sel_hi:[1,0]
	v_pk_mul_f32 v[94:95], v[94:95], v[126:127] op_sel_hi:[1,0]
	v_pk_mul_f32 v[96:97], v[96:97], v[126:127] op_sel_hi:[1,0]
	v_pk_mul_f32 v[82:83], v[82:83], v[126:127] op_sel_hi:[1,0]
	v_pk_mul_f32 v[84:85], v[84:85], v[126:127] op_sel_hi:[1,0]
	v_pk_mul_f32 v[86:87], v[86:87], v[126:127] op_sel_hi:[1,0]
	v_pk_mul_f32 v[88:89], v[88:89], v[126:127] op_sel_hi:[1,0]
	s_waitcnt lgkmcnt(1)
	v_pk_mul_f32 v[62:63], v[62:63], v[120:121] op_sel_hi:[1,0]
	v_pk_mul_f32 v[64:65], v[64:65], v[120:121] op_sel_hi:[1,0]
	v_pk_mul_f32 v[50:51], v[50:51], v[120:121] op_sel_hi:[1,0]
	v_pk_mul_f32 v[52:53], v[52:53], v[120:121] op_sel_hi:[1,0]
	v_pk_mul_f32 v[54:55], v[54:55], v[120:121] op_sel_hi:[1,0]
	v_pk_mul_f32 v[56:57], v[56:57], v[120:121] op_sel_hi:[1,0]
	s_waitcnt lgkmcnt(0)
	v_pk_mul_f32 v[32:33], v[32:33], v[118:119] op_sel_hi:[1,0]
	v_pk_mul_f32 v[28:29], v[28:29], v[118:119] op_sel_hi:[1,0]
	v_pk_mul_f32 v[22:23], v[22:23], v[118:119] op_sel_hi:[1,0]
	v_pk_mul_f32 v[24:25], v[24:25], v[118:119] op_sel_hi:[1,0]
	s_waitcnt vmcnt(3)
	v_pk_mul_f32 v[136:137], v[136:137], v[14:15]
	s_waitcnt vmcnt(2)
	v_pk_mul_f32 v[140:141], v[140:141], v[12:13]
	v_pk_mul_f32 v[138:139], v[138:139], v[10:11]
	v_pk_mul_f32 v[142:143], v[142:143], v[16:17]
	s_waitcnt vmcnt(1)
	v_pk_mul_f32 v[144:145], v[124:125], v[8:9]
	v_pk_mul_f32 v[160:161], v[122:123], v[6:7]
	v_mov_b32_dpp v178, v136 row_ror:8 row_mask:0xf bank_mask:0xf
	v_mov_b32_dpp v179, v138 row_ror:8 row_mask:0xf bank_mask:0xf
	v_mov_b32_dpp v181, v139 row_ror:8 row_mask:0xf bank_mask:0xf
	v_mov_b32_dpp v183, v140 row_ror:8 row_mask:0xf bank_mask:0xf
	v_mov_b32_dpp v185, v141 row_ror:8 row_mask:0xf bank_mask:0xf
	s_waitcnt vmcnt(0)
	v_pk_mul_f32 v[174:175], v[116:117], v[4:5]
	v_pk_mul_f32 v[176:177], v[114:115], v[2:3]
	v_mov_b32_dpp v180, v137 row_ror:8 row_mask:0xf bank_mask:0xf
	v_mov_b32_dpp v182, v142 row_ror:8 row_mask:0xf bank_mask:0xf
	v_mov_b32_dpp v184, v143 row_ror:8 row_mask:0xf bank_mask:0xf
	v_mov_b32_dpp v186, v160 row_ror:8 row_mask:0xf bank_mask:0xf
	v_mov_b32_dpp v188, v161 row_ror:8 row_mask:0xf bank_mask:0xf
	v_mov_b32_dpp v199, v144 row_ror:8 row_mask:0xf bank_mask:0xf
	v_mov_b32_dpp v201, v145 row_ror:8 row_mask:0xf bank_mask:0xf
	v_cndmask_b32_e32 v115, v181, v137, vcc
	v_cndmask_b32_e32 v114, v179, v136, vcc
	v_cndmask_b32_e32 v117, v185, v143, vcc
	v_cndmask_b32_e32 v116, v183, v142, vcc
	v_cndmask_b32_e32 v122, v138, v178, vcc
	v_cndmask_b32_e32 v123, v139, v180, vcc
	v_cndmask_b32_e32 v125, v141, v184, vcc
	v_cndmask_b32_e32 v124, v140, v182, vcc
	global_store_dwordx4 v128, v[114:117], s[24:25] nt
	s_bitset1_b32 s98, 0
	global_store_dwordx4 v198, v[122:125], s[24:25] nt
	s_bitset1_b32 s98, 1
	v_mov_b32_dpp v187, v176 row_ror:8 row_mask:0xf bank_mask:0xf
	v_cndmask_b32_e32 v115, v177, v188, vcc
	v_cndmask_b32_e32 v114, v176, v186, vcc
	v_cndmask_b32_e32 v117, v175, v201, vcc
	v_cndmask_b32_e32 v116, v174, v199, vcc
	v_add_u32_e32 v122, 0x8200, v128
	global_store_dwordx4 v122, v[114:117], s[24:25] nt
	s_bitset1_b32 s98, 2
	v_mov_b32_dpp v189, v177 row_ror:8 row_mask:0xf bank_mask:0xf
	v_mov_b32_dpp v200, v174 row_ror:8 row_mask:0xf bank_mask:0xf
	v_mov_b32_e32 v114, v173
	v_mov_b32_dpp v202, v175 row_ror:8 row_mask:0xf bank_mask:0xf
	v_pk_mul_f32 v[106:107], v[106:107], v[114:115] op_sel_hi:[1,0]
	v_pk_mul_f32 v[108:109], v[108:109], v[114:115] op_sel_hi:[1,0]
	v_cndmask_b32_e32 v137, v189, v161, vcc
	v_cndmask_b32_e32 v136, v187, v160, vcc
	v_cndmask_b32_e32 v139, v202, v145, vcc
	v_cndmask_b32_e32 v138, v200, v144, vcc
	v_pk_mul_f32 v[110:111], v[110:111], v[114:115] op_sel_hi:[1,0]
	v_pk_mul_f32 v[112:113], v[112:113], v[114:115] op_sel_hi:[1,0]
	v_pk_mul_f32 v[116:117], v[108:109], v[12:13]
	v_pk_mul_f32 v[122:123], v[106:107], v[10:11]
	v_mov_b32_e32 v106, 0
	v_mov_b32_e32 v107, 0
	v_mov_b32_e32 v108, 0
	v_mov_b32_e32 v109, 0
	global_store_dwordx4 v129, v[136:139], s[24:25] nt
	s_bitset1_b32 s98, 3
	v_pk_mul_f32 v[112:113], v[112:113], v[16:17]
	v_pk_mul_f32 v[110:111], v[110:111], v[14:15]
	v_mov_b32_e32 v124, 0
	v_mov_b32_dpp v106, v122 row_ror:8 row_mask:0xf bank_mask:0xf
	v_mov_b32_e32 v125, 0
	v_mov_b32_dpp v107, v123 row_ror:8 row_mask:0xf bank_mask:0xf
	v_mov_b32_e32 v129, 0
	v_mov_b32_dpp v108, v116 row_ror:8 row_mask:0xf bank_mask:0xf
	v_mov_b32_e32 v136, 0
	v_mov_b32_dpp v109, v117 row_ror:8 row_mask:0xf bank_mask:0xf
	v_add_u32_e32 v115, 0x10000, v128
	v_mov_b32_dpp v124, v110 row_ror:8 row_mask:0xf bank_mask:0xf
	v_mov_b32_dpp v125, v111 row_ror:8 row_mask:0xf bank_mask:0xf
	v_mov_b32_dpp v129, v112 row_ror:8 row_mask:0xf bank_mask:0xf
	v_mov_b32_dpp v136, v113 row_ror:8 row_mask:0xf bank_mask:0xf
	v_cndmask_b32_e32 v107, v107, v111, vcc
	v_cndmask_b32_e32 v106, v106, v110, vcc
	v_cndmask_b32_e32 v109, v109, v113, vcc
	v_cndmask_b32_e32 v108, v108, v112, vcc
	v_cndmask_b32_e32 v111, v123, v125, vcc
	v_cndmask_b32_e32 v110, v122, v124, vcc
	v_cndmask_b32_e32 v113, v117, v136, vcc
	v_cndmask_b32_e32 v112, v116, v129, vcc
	global_store_dwordx4 v115, v[106:109], s[24:25] nt
	s_bitset1_b32 s98, 4
	v_pk_mul_f32 v[98:99], v[98:99], v[114:115] op_sel_hi:[1,0]
	v_pk_mul_f32 v[100:101], v[100:101], v[114:115] op_sel_hi:[1,0]
	v_add_u32_e32 v106, 0x18000, v128
	global_store_dwordx4 v106, v[110:113], s[24:25] nt
	s_bitset1_b32 s98, 5
	v_pk_mul_f32 v[102:103], v[102:103], v[114:115] op_sel_hi:[1,0]
	v_pk_mul_f32 v[104:105], v[104:105], v[114:115] op_sel_hi:[1,0]
	v_pk_mul_f32 v[106:107], v[100:101], v[4:5]
	v_pk_mul_f32 v[108:109], v[98:99], v[2:3]
	v_mov_b32_e32 v98, 0
	v_mov_b32_e32 v99, 0
	v_mov_b32_e32 v100, 0
	v_mov_b32_e32 v101, 0
	v_pk_mul_f32 v[104:105], v[104:105], v[8:9]
	v_pk_mul_f32 v[102:103], v[102:103], v[6:7]
	v_mov_b32_e32 v111, 0
	v_mov_b32_dpp v98, v108 row_ror:8 row_mask:0xf bank_mask:0xf
	v_mov_b32_e32 v112, 0
	v_mov_b32_dpp v99, v109 row_ror:8 row_mask:0xf bank_mask:0xf
	v_mov_b32_e32 v113, 0
	v_mov_b32_dpp v100, v106 row_ror:8 row_mask:0xf bank_mask:0xf
	v_mov_b32_e32 v114, 0
	v_mov_b32_dpp v101, v107 row_ror:8 row_mask:0xf bank_mask:0xf
	v_add_u32_e32 v110, 0x10200, v128
	v_mov_b32_dpp v111, v102 row_ror:8 row_mask:0xf bank_mask:0xf
	v_mov_b32_dpp v112, v103 row_ror:8 row_mask:0xf bank_mask:0xf
	v_mov_b32_dpp v113, v104 row_ror:8 row_mask:0xf bank_mask:0xf
	v_mov_b32_dpp v114, v105 row_ror:8 row_mask:0xf bank_mask:0xf
	v_cndmask_b32_e32 v99, v99, v103, vcc
	v_cndmask_b32_e32 v98, v98, v102, vcc
	v_cndmask_b32_e32 v101, v101, v105, vcc
	v_cndmask_b32_e32 v100, v100, v104, vcc
	v_cndmask_b32_e32 v103, v109, v112, vcc
	v_cndmask_b32_e32 v102, v108, v111, vcc
	v_cndmask_b32_e32 v105, v107, v114, vcc
	v_cndmask_b32_e32 v104, v106, v113, vcc
	global_store_dwordx4 v110, v[98:101], s[24:25] nt
	s_bitset1_b32 s98, 6
	v_pk_mul_f32 v[96:97], v[96:97], v[16:17]
	v_pk_mul_f32 v[94:95], v[94:95], v[14:15]
	v_add_u32_e32 v98, 0x18200, v128
	global_store_dwordx4 v98, v[102:105], s[24:25] nt
	s_bitset1_b32 s98, 7
	v_pk_mul_f32 v[98:99], v[92:93], v[12:13]
	v_pk_mul_f32 v[100:101], v[90:91], v[10:11]
	v_mov_b32_e32 v90, 0
	v_mov_b32_e32 v91, 0
	v_mov_b32_e32 v92, 0
	v_mov_b32_e32 v93, 0
	v_mov_b32_e32 v103, 0
	v_mov_b32_dpp v90, v100 row_ror:8 row_mask:0xf bank_mask:0xf
	v_mov_b32_e32 v104, 0
	v_mov_b32_dpp v91, v101 row_ror:8 row_mask:0xf bank_mask:0xf
	v_mov_b32_e32 v105, 0
	v_mov_b32_dpp v92, v98 row_ror:8 row_mask:0xf bank_mask:0xf
	v_mov_b32_e32 v106, 0
	v_mov_b32_dpp v93, v99 row_ror:8 row_mask:0xf bank_mask:0xf
	v_add_u32_e32 v102, 0x20000, v128
	v_mov_b32_dpp v103, v94 row_ror:8 row_mask:0xf bank_mask:0xf
	v_mov_b32_dpp v104, v95 row_ror:8 row_mask:0xf bank_mask:0xf
	v_mov_b32_dpp v105, v96 row_ror:8 row_mask:0xf bank_mask:0xf
	v_mov_b32_dpp v106, v97 row_ror:8 row_mask:0xf bank_mask:0xf
	v_cndmask_b32_e32 v91, v91, v95, vcc
	v_cndmask_b32_e32 v90, v90, v94, vcc
	v_cndmask_b32_e32 v93, v93, v97, vcc
	v_cndmask_b32_e32 v92, v92, v96, vcc
	v_cndmask_b32_e32 v95, v101, v104, vcc
	v_cndmask_b32_e32 v94, v100, v103, vcc
	v_cndmask_b32_e32 v97, v99, v106, vcc
	v_cndmask_b32_e32 v96, v98, v105, vcc
	global_store_dwordx4 v102, v[90:93], s[24:25] nt
	s_bitset1_b32 s98, 8
	v_pk_mul_f32 v[88:89], v[88:89], v[8:9]
	v_pk_mul_f32 v[86:87], v[86:87], v[6:7]
	v_add_u32_e32 v90, 0x28000, v128
	global_store_dwordx4 v90, v[94:97], s[24:25] nt
	s_bitset1_b32 s98, 9
	v_pk_mul_f32 v[90:91], v[84:85], v[4:5]
	v_pk_mul_f32 v[92:93], v[82:83], v[2:3]
	v_mov_b32_e32 v82, 0
	v_mov_b32_e32 v83, 0
	v_mov_b32_e32 v84, 0
	v_mov_b32_e32 v85, 0
	v_mov_b32_e32 v95, 0
	v_mov_b32_dpp v82, v92 row_ror:8 row_mask:0xf bank_mask:0xf
	v_mov_b32_e32 v96, 0
	v_mov_b32_dpp v83, v93 row_ror:8 row_mask:0xf bank_mask:0xf
	v_mov_b32_e32 v97, 0
	v_mov_b32_dpp v84, v90 row_ror:8 row_mask:0xf bank_mask:0xf
	v_mov_b32_e32 v98, 0
	v_mov_b32_dpp v85, v91 row_ror:8 row_mask:0xf bank_mask:0xf
	v_add_u32_e32 v94, 0x20200, v128
	v_mov_b32_dpp v95, v86 row_ror:8 row_mask:0xf bank_mask:0xf
	v_mov_b32_dpp v96, v87 row_ror:8 row_mask:0xf bank_mask:0xf
	v_mov_b32_dpp v97, v88 row_ror:8 row_mask:0xf bank_mask:0xf
	v_mov_b32_dpp v98, v89 row_ror:8 row_mask:0xf bank_mask:0xf
	v_cndmask_b32_e32 v83, v83, v87, vcc
	v_cndmask_b32_e32 v82, v82, v86, vcc
	v_cndmask_b32_e32 v85, v85, v89, vcc
	v_cndmask_b32_e32 v84, v84, v88, vcc
	v_cndmask_b32_e32 v87, v93, v96, vcc
	v_cndmask_b32_e32 v86, v92, v95, vcc
	v_cndmask_b32_e32 v89, v91, v98, vcc
	v_cndmask_b32_e32 v88, v90, v97, vcc
	global_store_dwordx4 v94, v[82:85], s[24:25] nt
	s_bitset1_b32 s98, 10
	v_mov_b32_e32 v90, 0
	v_mov_b32_e32 v91, 0
	v_add_u32_e32 v82, 0x28200, v128
	global_store_dwordx4 v82, v[86:89], s[24:25] nt
	s_bitset1_b32 s98, 11
	v_mov_b32_e32 v82, v127
	v_pk_mul_f32 v[74:75], v[74:75], v[82:83] op_sel_hi:[1,0]
	v_pk_mul_f32 v[76:77], v[76:77], v[82:83] op_sel_hi:[1,0]
	v_pk_mul_f32 v[78:79], v[78:79], v[82:83] op_sel_hi:[1,0]
	v_pk_mul_f32 v[80:81], v[80:81], v[82:83] op_sel_hi:[1,0]
	v_pk_mul_f32 v[84:85], v[76:77], v[12:13]
	v_pk_mul_f32 v[86:87], v[74:75], v[10:11]
	v_mov_b32_e32 v74, 0
	v_mov_b32_e32 v75, 0
	v_mov_b32_e32 v76, 0
	v_mov_b32_e32 v77, 0
	v_pk_mul_f32 v[80:81], v[80:81], v[16:17]
	v_pk_mul_f32 v[78:79], v[78:79], v[14:15]
	v_mov_b32_e32 v88, 0
	v_mov_b32_dpp v74, v86 row_ror:8 row_mask:0xf bank_mask:0xf
	v_mov_b32_e32 v89, 0
	v_mov_b32_dpp v75, v87 row_ror:8 row_mask:0xf bank_mask:0xf
	v_mov_b32_dpp v76, v84 row_ror:8 row_mask:0xf bank_mask:0xf
	v_mov_b32_dpp v77, v85 row_ror:8 row_mask:0xf bank_mask:0xf
	v_add_u32_e32 v83, 0x30000, v128
	v_mov_b32_dpp v88, v78 row_ror:8 row_mask:0xf bank_mask:0xf
	v_mov_b32_dpp v89, v79 row_ror:8 row_mask:0xf bank_mask:0xf
	v_mov_b32_dpp v90, v80 row_ror:8 row_mask:0xf bank_mask:0xf
	v_mov_b32_dpp v91, v81 row_ror:8 row_mask:0xf bank_mask:0xf
	v_cndmask_b32_e32 v75, v75, v79, vcc
	v_cndmask_b32_e32 v74, v74, v78, vcc
	v_cndmask_b32_e32 v77, v77, v81, vcc
	v_cndmask_b32_e32 v76, v76, v80, vcc
	v_cndmask_b32_e32 v79, v87, v89, vcc
	v_cndmask_b32_e32 v78, v86, v88, vcc
	v_cndmask_b32_e32 v81, v85, v91, vcc
	v_cndmask_b32_e32 v80, v84, v90, vcc
	global_store_dwordx4 v83, v[74:77], s[24:25] nt
	s_bitset1_b32 s98, 12
	v_pk_mul_f32 v[66:67], v[66:67], v[82:83] op_sel_hi:[1,0]
	v_pk_mul_f32 v[68:69], v[68:69], v[82:83] op_sel_hi:[1,0]
	v_add_u32_e32 v74, 0x38000, v128
	global_store_dwordx4 v74, v[78:81], s[24:25] nt
	s_bitset1_b32 s98, 13
	v_pk_mul_f32 v[70:71], v[70:71], v[82:83] op_sel_hi:[1,0]
	v_pk_mul_f32 v[72:73], v[72:73], v[82:83] op_sel_hi:[1,0]
	v_pk_mul_f32 v[74:75], v[68:69], v[4:5]
	v_pk_mul_f32 v[76:77], v[66:67], v[2:3]
	v_mov_b32_e32 v66, 0
	v_mov_b32_e32 v67, 0
	v_mov_b32_e32 v68, 0
	v_mov_b32_e32 v69, 0
	v_pk_mul_f32 v[72:73], v[72:73], v[8:9]
	v_pk_mul_f32 v[70:71], v[70:71], v[6:7]
	v_mov_b32_e32 v79, 0
	v_mov_b32_dpp v66, v76 row_ror:8 row_mask:0xf bank_mask:0xf
	v_mov_b32_e32 v80, 0
	v_mov_b32_dpp v67, v77 row_ror:8 row_mask:0xf bank_mask:0xf
	v_mov_b32_e32 v81, 0
	v_mov_b32_dpp v68, v74 row_ror:8 row_mask:0xf bank_mask:0xf
	v_mov_b32_e32 v82, 0
	v_mov_b32_dpp v69, v75 row_ror:8 row_mask:0xf bank_mask:0xf
	v_add_u32_e32 v78, 0x30200, v128
	v_mov_b32_dpp v79, v70 row_ror:8 row_mask:0xf bank_mask:0xf
	v_mov_b32_dpp v80, v71 row_ror:8 row_mask:0xf bank_mask:0xf
	v_mov_b32_dpp v81, v72 row_ror:8 row_mask:0xf bank_mask:0xf
	v_mov_b32_dpp v82, v73 row_ror:8 row_mask:0xf bank_mask:0xf
	v_cndmask_b32_e32 v67, v67, v71, vcc
	v_cndmask_b32_e32 v66, v66, v70, vcc
	v_cndmask_b32_e32 v69, v69, v73, vcc
	v_cndmask_b32_e32 v68, v68, v72, vcc
	v_cndmask_b32_e32 v71, v77, v80, vcc
	v_cndmask_b32_e32 v70, v76, v79, vcc
	v_cndmask_b32_e32 v73, v75, v82, vcc
	v_cndmask_b32_e32 v72, v74, v81, vcc
	global_store_dwordx4 v78, v[66:69], s[24:25] nt
	s_bitset1_b32 s98, 14
	v_mov_b32_e32 v75, 0
	v_mov_b32_e32 v76, 0
	v_add_u32_e32 v66, 0x38200, v128
	global_store_dwordx4 v66, v[70:73], s[24:25] nt
	s_bitset1_b32 s98, 15
	v_pk_mul_f32 v[66:67], v[170:171], v[120:121] op_sel_hi:[1,0]
	v_pk_mul_f32 v[68:69], v[166:167], v[120:121] op_sel_hi:[1,0]
	v_pk_mul_f32 v[70:71], v[64:65], v[12:13]
	v_pk_mul_f32 v[72:73], v[62:63], v[10:11]
	v_mov_b32_e32 v62, 0
	v_mov_b32_e32 v63, 0
	v_mov_b32_e32 v64, 0
	v_mov_b32_e32 v65, 0
	v_pk_mul_f32 v[68:69], v[68:69], v[16:17]
	v_pk_mul_f32 v[66:67], v[66:67], v[14:15]
	v_mov_b32_dpp v62, v72 row_ror:8 row_mask:0xf bank_mask:0xf
	v_mov_b32_dpp v63, v73 row_ror:8 row_mask:0xf bank_mask:0xf
	v_mov_b32_e32 v77, 0
	v_mov_b32_dpp v64, v70 row_ror:8 row_mask:0xf bank_mask:0xf
	v_mov_b32_e32 v78, 0
	v_mov_b32_dpp v65, v71 row_ror:8 row_mask:0xf bank_mask:0xf
	v_add_u32_e32 v74, 0x80000, v128
	v_mov_b32_dpp v75, v66 row_ror:8 row_mask:0xf bank_mask:0xf
	v_mov_b32_dpp v76, v67 row_ror:8 row_mask:0xf bank_mask:0xf
	v_mov_b32_dpp v77, v68 row_ror:8 row_mask:0xf bank_mask:0xf
	v_mov_b32_dpp v78, v69 row_ror:8 row_mask:0xf bank_mask:0xf
	v_cndmask_b32_e32 v63, v63, v67, vcc
	v_cndmask_b32_e32 v62, v62, v66, vcc
	v_cndmask_b32_e32 v65, v65, v69, vcc
	v_cndmask_b32_e32 v64, v64, v68, vcc
	v_cndmask_b32_e32 v67, v73, v76, vcc
	v_cndmask_b32_e32 v66, v72, v75, vcc
	v_cndmask_b32_e32 v69, v71, v78, vcc
	v_cndmask_b32_e32 v68, v70, v77, vcc
	global_store_dwordx4 v74, v[62:65], s[24:25] nt
	s_bitset1_b32 s98, 16
	v_pk_mul_f32 v[56:57], v[56:57], v[8:9]
	v_pk_mul_f32 v[54:55], v[54:55], v[6:7]
	v_add_u32_e32 v62, 0x88000, v128
	global_store_dwordx4 v62, v[66:69], s[24:25] nt
	s_bitset1_b32 s98, 17
	v_pk_mul_f32 v[62:63], v[52:53], v[4:5]
	v_pk_mul_f32 v[64:65], v[50:51], v[2:3]
	v_mov_b32_e32 v50, 0
	v_mov_b32_e32 v51, 0
	v_mov_b32_e32 v52, 0
	v_mov_b32_e32 v53, 0
	v_mov_b32_e32 v67, 0
	v_mov_b32_dpp v50, v64 row_ror:8 row_mask:0xf bank_mask:0xf
	v_mov_b32_e32 v68, 0
	v_mov_b32_dpp v51, v65 row_ror:8 row_mask:0xf bank_mask:0xf
	v_mov_b32_e32 v69, 0
	v_mov_b32_dpp v52, v62 row_ror:8 row_mask:0xf bank_mask:0xf
	v_mov_b32_e32 v70, 0
	v_mov_b32_dpp v53, v63 row_ror:8 row_mask:0xf bank_mask:0xf
	v_add_u32_e32 v66, 0x80200, v128
	v_mov_b32_dpp v67, v54 row_ror:8 row_mask:0xf bank_mask:0xf
	v_mov_b32_dpp v68, v55 row_ror:8 row_mask:0xf bank_mask:0xf
	v_mov_b32_dpp v69, v56 row_ror:8 row_mask:0xf bank_mask:0xf
	v_mov_b32_dpp v70, v57 row_ror:8 row_mask:0xf bank_mask:0xf
	v_cndmask_b32_e32 v51, v51, v55, vcc
	v_cndmask_b32_e32 v50, v50, v54, vcc
	v_cndmask_b32_e32 v53, v53, v57, vcc
	v_cndmask_b32_e32 v52, v52, v56, vcc
	v_cndmask_b32_e32 v55, v65, v68, vcc
	v_cndmask_b32_e32 v54, v64, v67, vcc
	v_cndmask_b32_e32 v57, v63, v70, vcc
	v_cndmask_b32_e32 v56, v62, v69, vcc
	global_store_dwordx4 v66, v[50:53], s[24:25] nt
	s_bitset1_b32 s98, 18
	v_mov_b32_e32 v63, 0
	v_mov_b32_e32 v65, 0
	v_add_u32_e32 v50, 0x88200, v128
	global_store_dwordx4 v50, v[54:57], s[24:25] nt
	s_bitset1_b32 s98, 19
	v_mov_b32_e32 v62, 0
	v_mov_b32_e32 v64, 0
	v_mov_b32_e32 v56, v121
	v_pk_mul_f32 v[50:51], v[58:59], v[56:57] op_sel_hi:[1,0]
	v_pk_mul_f32 v[48:49], v[48:49], v[56:57] op_sel_hi:[1,0]
	v_pk_mul_f32 v[54:55], v[60:61], v[56:57] op_sel_hi:[1,0]
	v_pk_mul_f32 v[52:53], v[48:49], v[16:17]
	v_pk_mul_f32 v[48:49], v[50:51], v[14:15]
	v_pk_mul_f32 v[50:51], v[164:165], v[56:57] op_sel_hi:[1,0]
	v_pk_mul_f32 v[54:55], v[54:55], v[12:13]
	v_pk_mul_f32 v[58:59], v[50:51], v[10:11]
	v_mov_b32_e32 v50, 0
	v_mov_b32_e32 v51, 0
	v_mov_b32_e32 v60, 0
	v_mov_b32_dpp v50, v58 row_ror:8 row_mask:0xf bank_mask:0xf
	v_mov_b32_e32 v61, 0
	v_mov_b32_dpp v51, v59 row_ror:8 row_mask:0xf bank_mask:0xf
	v_mov_b32_dpp v63, v54 row_ror:8 row_mask:0xf bank_mask:0xf
	v_mov_b32_dpp v65, v55 row_ror:8 row_mask:0xf bank_mask:0xf
	v_add_u32_e32 v57, 0x90000, v128
	v_mov_b32_dpp v60, v48 row_ror:8 row_mask:0xf bank_mask:0xf
	v_mov_b32_dpp v61, v49 row_ror:8 row_mask:0xf bank_mask:0xf
	v_mov_b32_dpp v62, v52 row_ror:8 row_mask:0xf bank_mask:0xf
	v_mov_b32_dpp v64, v53 row_ror:8 row_mask:0xf bank_mask:0xf
	v_cndmask_b32_e32 v49, v51, v49, vcc
	v_cndmask_b32_e32 v48, v50, v48, vcc
	v_cndmask_b32_e32 v51, v65, v53, vcc
	v_cndmask_b32_e32 v50, v63, v52, vcc
	v_cndmask_b32_e32 v53, v59, v61, vcc
	v_cndmask_b32_e32 v52, v58, v60, vcc
	v_cndmask_b32_e32 v55, v55, v64, vcc
	v_cndmask_b32_e32 v54, v54, v62, vcc
	global_store_dwordx4 v57, v[48:51], s[24:25] nt
	s_bitset1_b32 s98, 20
	v_pk_mul_f32 v[34:35], v[34:35], v[56:57] op_sel_hi:[1,0]
	v_pk_mul_f32 v[36:37], v[36:37], v[56:57] op_sel_hi:[1,0]
	v_add_u32_e32 v48, 0x98000, v128
	global_store_dwordx4 v48, v[52:55], s[24:25] nt
	s_bitset1_b32 s98, 21
	v_pk_mul_f32 v[38:39], v[38:39], v[56:57] op_sel_hi:[1,0]
	v_pk_mul_f32 v[40:41], v[40:41], v[56:57] op_sel_hi:[1,0]
	v_pk_mul_f32 v[48:49], v[36:37], v[4:5]
	v_pk_mul_f32 v[50:51], v[34:35], v[2:3]
	v_mov_b32_e32 v34, 0
	v_mov_b32_e32 v35, 0
	v_mov_b32_e32 v36, 0
	v_mov_b32_e32 v37, 0
	v_pk_mul_f32 v[40:41], v[40:41], v[8:9]
	v_pk_mul_f32 v[38:39], v[38:39], v[6:7]
	v_mov_b32_e32 v53, 0
	v_mov_b32_dpp v34, v50 row_ror:8 row_mask:0xf bank_mask:0xf
	v_mov_b32_e32 v54, 0
	v_mov_b32_dpp v35, v51 row_ror:8 row_mask:0xf bank_mask:0xf
	v_mov_b32_e32 v55, 0
	v_mov_b32_dpp v36, v48 row_ror:8 row_mask:0xf bank_mask:0xf
	v_mov_b32_e32 v56, 0
	v_mov_b32_dpp v37, v49 row_ror:8 row_mask:0xf bank_mask:0xf
	v_add_u32_e32 v52, 0x90200, v128
	v_mov_b32_dpp v53, v38 row_ror:8 row_mask:0xf bank_mask:0xf
	v_mov_b32_dpp v54, v39 row_ror:8 row_mask:0xf bank_mask:0xf
	v_mov_b32_dpp v55, v40 row_ror:8 row_mask:0xf bank_mask:0xf
	v_mov_b32_dpp v56, v41 row_ror:8 row_mask:0xf bank_mask:0xf
	v_cndmask_b32_e32 v35, v35, v39, vcc
	v_cndmask_b32_e32 v34, v34, v38, vcc
	v_cndmask_b32_e32 v37, v37, v41, vcc
	v_cndmask_b32_e32 v36, v36, v40, vcc
	v_cndmask_b32_e32 v39, v51, v54, vcc
	v_cndmask_b32_e32 v38, v50, v53, vcc
	v_cndmask_b32_e32 v41, v49, v56, vcc
	v_cndmask_b32_e32 v40, v48, v55, vcc
	global_store_dwordx4 v52, v[34:37], s[24:25] nt
	s_bitset1_b32 s98, 22
	v_mov_b32_e32 v50, 0
	v_mov_b32_e32 v52, 0
	v_add_u32_e32 v34, 0x98200, v128
	global_store_dwordx4 v34, v[38:41], s[24:25] nt
	s_bitset1_b32 s98, 23
	v_pk_mul_f32 v[34:35], v[46:47], v[118:119] op_sel_hi:[1,0]
	v_pk_mul_f32 v[36:37], v[16:17], v[32:33]
	v_pk_mul_f32 v[32:33], v[14:15], v[34:35]
	v_pk_mul_f32 v[34:35], v[168:169], v[118:119] op_sel_hi:[1,0]
	v_pk_mul_f32 v[38:39], v[162:163], v[118:119] op_sel_hi:[1,0]
	v_pk_mul_f32 v[40:41], v[34:35], v[10:11]
	v_pk_mul_f32 v[38:39], v[38:39], v[12:13]
	v_mov_b32_e32 v34, 0
	v_mov_b32_e32 v35, 0
	v_mov_b32_e32 v47, 0
	v_mov_b32_dpp v34, v40 row_ror:8 row_mask:0xf bank_mask:0xf
	v_mov_b32_e32 v48, 0
	v_mov_b32_dpp v35, v41 row_ror:8 row_mask:0xf bank_mask:0xf
	v_mov_b32_e32 v49, 0
	v_mov_b32_dpp v50, v38 row_ror:8 row_mask:0xf bank_mask:0xf
	v_mov_b32_e32 v51, 0
	v_mov_b32_dpp v52, v39 row_ror:8 row_mask:0xf bank_mask:0xf
	v_add_u32_e32 v46, 0xa0000, v128
	v_mov_b32_dpp v47, v32 row_ror:8 row_mask:0xf bank_mask:0xf
	v_mov_b32_dpp v48, v33 row_ror:8 row_mask:0xf bank_mask:0xf
	v_mov_b32_dpp v49, v36 row_ror:8 row_mask:0xf bank_mask:0xf
	v_mov_b32_dpp v51, v37 row_ror:8 row_mask:0xf bank_mask:0xf
	v_cndmask_b32_e32 v33, v35, v33, vcc
	v_cndmask_b32_e32 v32, v34, v32, vcc
	v_cndmask_b32_e32 v35, v52, v37, vcc
	v_cndmask_b32_e32 v34, v50, v36, vcc
	v_cndmask_b32_e32 v37, v41, v48, vcc
	v_cndmask_b32_e32 v36, v40, v47, vcc
	v_cndmask_b32_e32 v39, v39, v51, vcc
	v_cndmask_b32_e32 v38, v38, v49, vcc
	global_store_dwordx4 v46, v[32:35], s[24:25] nt
	s_bitset1_b32 s98, 24
	v_pk_mul_f32 v[28:29], v[28:29], v[4:5]
	v_mov_b32_e32 v40, 0
	v_add_u32_e32 v32, 0xa8000, v128
	global_store_dwordx4 v32, v[36:39], s[24:25] nt
	s_bitset1_b32 s98, 25
	v_pk_mul_f32 v[32:33], v[44:45], v[118:119] op_sel_hi:[1,0]
	v_mov_b32_e32 v35, 0
	v_pk_mul_f32 v[32:33], v[32:33], v[2:3]
	v_mov_b32_e32 v38, 0
	v_mov_b32_e32 v44, 0
	v_pk_mul_f32 v[24:25], v[24:25], v[8:9]
	v_pk_mul_f32 v[22:23], v[22:23], v[6:7]
	v_mov_b32_e32 v34, 0
	v_mov_b32_dpp v35, v32 row_ror:8 row_mask:0xf bank_mask:0xf
	v_mov_b32_e32 v37, 0
	v_mov_b32_dpp v38, v33 row_ror:8 row_mask:0xf bank_mask:0xf
	v_mov_b32_e32 v39, 0
	v_mov_b32_dpp v40, v28 row_ror:8 row_mask:0xf bank_mask:0xf
	v_mov_b32_e32 v41, 0
	v_mov_b32_dpp v44, v29 row_ror:8 row_mask:0xf bank_mask:0xf
	v_add_u32_e32 v36, 0xa0200, v128
	v_mov_b32_dpp v34, v22 row_ror:8 row_mask:0xf bank_mask:0xf
	v_mov_b32_dpp v37, v23 row_ror:8 row_mask:0xf bank_mask:0xf
	v_mov_b32_dpp v39, v24 row_ror:8 row_mask:0xf bank_mask:0xf
	v_mov_b32_dpp v41, v25 row_ror:8 row_mask:0xf bank_mask:0xf
	v_cndmask_b32_e32 v23, v38, v23, vcc
	v_cndmask_b32_e32 v22, v35, v22, vcc
	v_cndmask_b32_e32 v25, v44, v25, vcc
	v_cndmask_b32_e32 v24, v40, v24, vcc
	v_cndmask_b32_e32 v33, v33, v37, vcc
	v_cndmask_b32_e32 v32, v32, v34, vcc
	v_cndmask_b32_e32 v35, v29, v41, vcc
	v_cndmask_b32_e32 v34, v28, v39, vcc
	global_store_dwordx4 v36, v[22:25], s[24:25] nt
	s_bitset1_b32 s98, 26
	s_nop 1
	v_add_u32_e32 v22, 0xa8200, v128
	global_store_dwordx4 v22, v[32:35], s[24:25] nt
	s_bitset1_b32 s98, 27
	v_mov_b32_e32 v22, v119
	v_pk_mul_f32 v[24:25], v[134:135], v[22:23] op_sel_hi:[1,0]
	v_pk_mul_f32 v[28:29], v[42:43], v[22:23] op_sel_hi:[1,0]
	v_pk_mul_f32 v[14:15], v[14:15], v[24:25]
	v_pk_mul_f32 v[16:17], v[16:17], v[28:29]
	v_pk_mul_f32 v[24:25], v[130:131], v[22:23] op_sel_hi:[1,0]
	v_pk_mul_f32 v[28:29], v[132:133], v[22:23] op_sel_hi:[1,0]
	v_pk_mul_f32 v[24:25], v[10:11], v[24:25]
	v_pk_mul_f32 v[28:29], v[12:13], v[28:29]
	v_mov_b32_e32 v10, 0
	v_mov_b32_e32 v11, 0
	v_mov_b32_e32 v12, 0
	v_mov_b32_e32 v13, 0
	v_mov_b32_e32 v32, 0
	v_mov_b32_dpp v10, v24 row_ror:8 row_mask:0xf bank_mask:0xf
	v_mov_b32_e32 v33, 0
	v_mov_b32_dpp v11, v25 row_ror:8 row_mask:0xf bank_mask:0xf
	v_mov_b32_e32 v34, 0
	v_mov_b32_dpp v12, v28 row_ror:8 row_mask:0xf bank_mask:0xf
	v_mov_b32_e32 v35, 0
	v_mov_b32_dpp v13, v29 row_ror:8 row_mask:0xf bank_mask:0xf
	v_add_u32_e32 v23, 0xb0000, v128
	v_mov_b32_dpp v32, v14 row_ror:8 row_mask:0xf bank_mask:0xf
	v_mov_b32_dpp v33, v15 row_ror:8 row_mask:0xf bank_mask:0xf
	v_mov_b32_dpp v34, v16 row_ror:8 row_mask:0xf bank_mask:0xf
	v_mov_b32_dpp v35, v17 row_ror:8 row_mask:0xf bank_mask:0xf
	v_cndmask_b32_e32 v11, v11, v15, vcc
	v_cndmask_b32_e32 v10, v10, v14, vcc
	v_cndmask_b32_e32 v13, v13, v17, vcc
	v_cndmask_b32_e32 v12, v12, v16, vcc
	v_cndmask_b32_e32 v15, v25, v33, vcc
	v_cndmask_b32_e32 v14, v24, v32, vcc
	v_cndmask_b32_e32 v17, v29, v35, vcc
	v_cndmask_b32_e32 v16, v28, v34, vcc
	global_store_dwordx4 v23, v[10:13], s[24:25] nt
	s_bitset1_b32 s98, 28
	s_nop 1
	v_add_u32_e32 v10, 0xb8000, v128
	global_store_dwordx4 v10, v[14:17], s[24:25] nt
	s_bitset1_b32 s98, 29
	v_pk_mul_f32 v[10:11], v[20:21], v[22:23] op_sel_hi:[1,0]
	v_pk_mul_f32 v[12:13], v[18:19], v[22:23] op_sel_hi:[1,0]
	v_pk_mul_f32 v[6:7], v[10:11], v[6:7]
	v_pk_mul_f32 v[8:9], v[12:13], v[8:9]
	v_pk_mul_f32 v[10:11], v[30:31], v[22:23] op_sel_hi:[1,0]
	v_pk_mul_f32 v[12:13], v[26:27], v[22:23] op_sel_hi:[1,0]
	v_pk_mul_f32 v[10:11], v[10:11], v[2:3]
	v_pk_mul_f32 v[12:13], v[12:13], v[4:5]
	v_mov_b32_e32 v2, 0
	v_mov_b32_e32 v3, 0
	v_mov_b32_e32 v4, 0
	v_mov_b32_e32 v5, 0
	v_mov_b32_e32 v15, 0
	v_mov_b32_dpp v2, v10 row_ror:8 row_mask:0xf bank_mask:0xf
	v_mov_b32_e32 v16, 0
	v_mov_b32_dpp v3, v11 row_ror:8 row_mask:0xf bank_mask:0xf
	v_mov_b32_e32 v17, 0
	v_mov_b32_dpp v4, v12 row_ror:8 row_mask:0xf bank_mask:0xf
	v_mov_b32_e32 v18, 0
	v_mov_b32_dpp v5, v13 row_ror:8 row_mask:0xf bank_mask:0xf
	v_add_u32_e32 v14, 0xb0200, v128
	v_mov_b32_dpp v15, v6 row_ror:8 row_mask:0xf bank_mask:0xf
	v_mov_b32_dpp v16, v7 row_ror:8 row_mask:0xf bank_mask:0xf
	v_mov_b32_dpp v17, v8 row_ror:8 row_mask:0xf bank_mask:0xf
	v_mov_b32_dpp v18, v9 row_ror:8 row_mask:0xf bank_mask:0xf
	v_cndmask_b32_e32 v3, v3, v7, vcc
	v_cndmask_b32_e32 v2, v2, v6, vcc
	v_cndmask_b32_e32 v5, v5, v9, vcc
	v_cndmask_b32_e32 v4, v4, v8, vcc
	v_cndmask_b32_e32 v7, v11, v16, vcc
	v_cndmask_b32_e32 v6, v10, v15, vcc
	v_cndmask_b32_e32 v9, v13, v18, vcc
	v_cndmask_b32_e32 v8, v12, v17, vcc
	global_store_dwordx4 v14, v[2:5], s[24:25] nt
	s_bitset1_b32 s98, 30
	s_andn2_b64 vcc, exec, s[0:1]
	s_mov_b64 s[0:1], -1
	v_add_u32_e32 v2, 0xb8200, v128
	global_store_dwordx4 v2, v[6:9], s[24:25] nt
	s_bitset1_b32 s98, 31
	s_cbranch_vccnz .LBB0_847
	s_andn2_b64 vcc, exec, s[12:13]
	s_cbranch_vccnz .LBB0_846
	s_barrier
	s_branch .LBB0_846
.Lrwp7_first:
	ds_read_b128 v[118:121], v193
	ds_read_b128 v[126:129], v193 offset:1024
	ds_read_b128 v[130:133], v193 offset:2048
	ds_read_b128 v[134:137], v193 offset:3072
	ds_read_b128 v[160:163], v194
	ds_read_b128 v[164:167], v194 offset:1024
	ds_read_b128 v[168:171], v194 offset:2048
	ds_read_b128 v[172:175], v194 offset:3072
	s_add_u32 s8, s4, 0xfff00080
	s_addc_u32 s9, s5, -1
	s_cmp_eq_u32 s61, 60
	s_cselect_b32 s59, s7, s9
	s_cselect_b32 s58, s10, s8
	s_cselect_b32 s9, s49, s60
	s_cselect_b32 s8, s51, s57
	v_lshl_add_u64 v[188:189], s[4:5], 0, v[150:151]
	s_add_i32 m0, s64, 0xc000
	ds_read_b128 v[176:179], v195
	ds_read_b128 v[180:183], v195 offset:1024
	ds_read_b128 v[184:187], v195 offset:2048
	ds_read_b128 v[198:201], v195 offset:3072
	ds_read_b128 v[202:205], v195 offset:4096
	ds_read_b128 v[206:209], v195 offset:5120
	ds_read_b128 v[210:213], v195 offset:6144
	ds_read_b128 v[214:217], v195 offset:7168
	global_load_lds_dwordx4 v[188:189], off
	v_lshl_add_u64 v[188:189], s[4:5], 0, v[152:153]
	s_add_i32 m0, s64, 0xe000
	s_nop 0
	global_load_lds_dwordx4 v[188:189], off
	s_cmp_eq_u32 s98, -1
	s_cbranch_scc1 .Lrwp7_a32
	s_waitcnt vmcnt(8)
	s_branch .Lrwp7_adone

.Lrwp7_adone:
	s_waitcnt lgkmcnt(0)
	s_barrier
	s_setprio 1
	s_waitcnt lgkmcnt(0)
	v_mfma_f32_16x16x32_bf16 v[142:145], v[118:121], v[176:179], v[142:145]
	v_mfma_f32_16x16x32_bf16 v[138:141], v[130:133], v[176:179], v[138:141]
	v_mfma_f32_16x16x32_bf16 v[110:113], v[118:121], v[184:187], v[110:113]
	v_mfma_f32_16x16x32_bf16 v[106:109], v[130:133], v[184:187], v[106:109]
	v_mfma_f32_16x16x32_bf16 v[94:97], v[118:121], v[202:205], v[94:97]
	v_mfma_f32_16x16x32_bf16 v[90:93], v[130:133], v[202:205], v[90:93]
	v_mfma_f32_16x16x32_bf16 v[78:81], v[118:121], v[210:213], v[78:81]
	v_mfma_f32_16x16x32_bf16 v[74:77], v[130:133], v[210:213], v[74:77]
	v_mfma_f32_16x16x32_bf16 v[142:145], v[126:129], v[180:183], v[142:145]
	v_mfma_f32_16x16x32_bf16 v[138:141], v[134:137], v[180:183], v[138:141]
	v_mfma_f32_16x16x32_bf16 v[110:113], v[126:129], v[198:201], v[110:113]
	v_mfma_f32_16x16x32_bf16 v[106:109], v[134:137], v[198:201], v[106:109]
	v_mfma_f32_16x16x32_bf16 v[94:97], v[126:129], v[206:209], v[94:97]
	v_mfma_f32_16x16x32_bf16 v[90:93], v[134:137], v[206:209], v[90:93]
	v_mfma_f32_16x16x32_bf16 v[78:81], v[126:129], v[214:217], v[78:81]
	v_mfma_f32_16x16x32_bf16 v[74:77], v[134:137], v[214:217], v[74:77]
	s_setprio 0
	s_setprio 1
	v_mfma_f32_16x16x32_bf16 v[122:125], v[160:163], v[176:179], v[122:125]
	v_mfma_f32_16x16x32_bf16 v[114:117], v[168:171], v[176:179], v[114:117]
	v_mfma_f32_16x16x32_bf16 v[102:105], v[160:163], v[184:187], v[102:105]
	v_mfma_f32_16x16x32_bf16 v[98:101], v[168:171], v[184:187], v[98:101]
	v_mfma_f32_16x16x32_bf16 v[86:89], v[160:163], v[202:205], v[86:89]
	v_mfma_f32_16x16x32_bf16 v[82:85], v[168:171], v[202:205], v[82:85]
	v_mfma_f32_16x16x32_bf16 v[70:73], v[160:163], v[210:213], v[70:73]
	v_mfma_f32_16x16x32_bf16 v[66:69], v[168:171], v[210:213], v[66:69]
	v_mfma_f32_16x16x32_bf16 v[122:125], v[164:167], v[180:183], v[122:125]
	v_mfma_f32_16x16x32_bf16 v[114:117], v[172:175], v[180:183], v[114:117]
	v_mfma_f32_16x16x32_bf16 v[102:105], v[164:167], v[198:201], v[102:105]
	v_mfma_f32_16x16x32_bf16 v[98:101], v[172:175], v[198:201], v[98:101]
	v_mfma_f32_16x16x32_bf16 v[86:89], v[164:167], v[206:209], v[86:89]
	v_mfma_f32_16x16x32_bf16 v[82:85], v[172:175], v[206:209], v[82:85]
	v_mfma_f32_16x16x32_bf16 v[70:73], v[164:167], v[214:217], v[70:73]
	v_mfma_f32_16x16x32_bf16 v[66:69], v[172:175], v[214:217], v[66:69]
	s_setprio 0
	s_barrier
	s_add_i32 s62, s84, s33
	v_lshl_add_u64 v[188:189], s[8:9], 0, v[146:147]
	s_mov_b32 m0, s62
	ds_read_b128 v[176:179], v195 offset:16384
	ds_read_b128 v[180:183], v195 offset:17408
	ds_read_b128 v[184:187], v195 offset:18432
	ds_read_b128 v[198:201], v195 offset:19456
	ds_read_b128 v[202:205], v195 offset:20480
	ds_read_b128 v[206:209], v195 offset:21504
	ds_read_b128 v[210:213], v195 offset:22528
	ds_read_b128 v[214:217], v195 offset:23552
	global_load_lds_dwordx4 v[188:189], off
	s_add_i32 m0, s62, 0x2000
	s_add_u32 s62, s8, 0x100000
	v_lshl_add_u64 v[218:219], s[8:9], 0, v[148:149]
	s_addc_u32 s63, s9, 0
	s_add_i32 s92, s85, s33
	global_load_lds_dwordx4 v[218:219], off
	v_lshl_add_u64 v[220:221], s[62:63], 0, v[146:147]
	s_mov_b32 m0, s92
	v_lshl_add_u64 v[222:223], s[58:59], 0, v[148:149]
	global_load_lds_dwordx4 v[220:221], off
	v_lshl_add_u64 v[220:221], s[62:63], 0, v[148:149]
	s_add_i32 m0, s92, 0x2000
	s_nop 0
	global_load_lds_dwordx4 v[220:221], off
	v_lshl_add_u64 v[220:221], s[58:59], 0, v[146:147]
	s_mov_b32 m0, s64
	s_nop 0
	global_load_lds_dwordx4 v[220:221], off
	s_mov_b32 m0, s65
	s_nop 0
	global_load_lds_dwordx4 v[222:223], off
	s_cmp_eq_u32 s98, -1
	s_cbranch_scc1 .Lrwp7_b32
	s_waitcnt vmcnt(8)
	s_branch .Lrwp7_bdone

.Lrwp7_bdone:
	s_mov_b32 s98, 0
	s_waitcnt lgkmcnt(0)
	s_barrier
	s_setprio 1
	s_waitcnt lgkmcnt(0)
	v_mfma_f32_16x16x32_bf16 v[58:61], v[118:121], v[176:179], v[58:61]
	v_mfma_f32_16x16x32_bf16 v[62:65], v[130:133], v[176:179], v[62:65]
	v_mfma_f32_16x16x32_bf16 v[46:49], v[118:121], v[184:187], v[46:49]
	v_mfma_f32_16x16x32_bf16 v[42:45], v[130:133], v[184:187], v[42:45]
	v_mfma_f32_16x16x32_bf16 v[30:33], v[118:121], v[202:205], v[30:33]
	v_mfma_f32_16x16x32_bf16 v[26:29], v[130:133], v[202:205], v[26:29]
	v_mfma_f32_16x16x32_bf16 v[14:17], v[118:121], v[210:213], v[14:17]
	v_mfma_f32_16x16x32_bf16 v[10:13], v[130:133], v[210:213], v[10:13]
	v_mfma_f32_16x16x32_bf16 v[58:61], v[126:129], v[180:183], v[58:61]
	v_mfma_f32_16x16x32_bf16 v[62:65], v[134:137], v[180:183], v[62:65]
	v_mfma_f32_16x16x32_bf16 v[46:49], v[126:129], v[198:201], v[46:49]
	v_mfma_f32_16x16x32_bf16 v[42:45], v[134:137], v[198:201], v[42:45]
	v_mfma_f32_16x16x32_bf16 v[30:33], v[126:129], v[206:209], v[30:33]
	v_mfma_f32_16x16x32_bf16 v[26:29], v[134:137], v[206:209], v[26:29]
	v_mfma_f32_16x16x32_bf16 v[14:17], v[126:129], v[214:217], v[14:17]
	v_mfma_f32_16x16x32_bf16 v[10:13], v[134:137], v[214:217], v[10:13]
	s_setprio 0
	s_setprio 1
	v_mfma_f32_16x16x32_bf16 v[54:57], v[160:163], v[176:179], v[54:57]
	v_mfma_f32_16x16x32_bf16 v[50:53], v[168:171], v[176:179], v[50:53]
	v_mfma_f32_16x16x32_bf16 v[38:41], v[160:163], v[184:187], v[38:41]
	v_mfma_f32_16x16x32_bf16 v[34:37], v[168:171], v[184:187], v[34:37]
	v_mfma_f32_16x16x32_bf16 v[22:25], v[160:163], v[202:205], v[22:25]
	v_mfma_f32_16x16x32_bf16 v[18:21], v[168:171], v[202:205], v[18:21]
	v_mfma_f32_16x16x32_bf16 v[6:9], v[160:163], v[210:213], v[6:9]
	v_mfma_f32_16x16x32_bf16 v[2:5], v[168:171], v[210:213], v[2:5]
	v_mfma_f32_16x16x32_bf16 v[54:57], v[164:167], v[180:183], v[54:57]
	v_mfma_f32_16x16x32_bf16 v[50:53], v[172:175], v[180:183], v[50:53]
	v_mfma_f32_16x16x32_bf16 v[38:41], v[164:167], v[198:201], v[38:41]
	v_mfma_f32_16x16x32_bf16 v[34:37], v[172:175], v[198:201], v[34:37]
	v_mfma_f32_16x16x32_bf16 v[22:25], v[164:167], v[206:209], v[22:25]
	v_mfma_f32_16x16x32_bf16 v[18:21], v[172:175], v[206:209], v[18:21]
	v_mfma_f32_16x16x32_bf16 v[6:9], v[164:167], v[214:217], v[6:9]
	v_mfma_f32_16x16x32_bf16 v[2:5], v[172:175], v[214:217], v[2:5]
	s_setprio 0
	s_barrier
	s_add_i32 s62, 0, 0x18000
	s_add_i32 s63, 0, 0x1c000
	v_add_u32_e32 v134, s62, v192
	v_add_u32_e32 v172, s63, v192
	ds_read_b128 v[118:121], v134
	ds_read_b128 v[126:129], v134 offset:1024
	ds_read_b128 v[130:133], v134 offset:2048
	ds_read_b128 v[134:137], v134 offset:3072
	ds_read_b128 v[160:163], v172
	ds_read_b128 v[164:167], v172 offset:1024
	ds_read_b128 v[168:171], v172 offset:2048
	ds_read_b128 v[172:175], v172 offset:3072
	s_add_u32 s58, s58, 0x100000
	s_addc_u32 s59, s59, 0
	s_mov_b32 m0, s66
	v_lshl_add_u64 v[224:225], s[58:59], 0, v[146:147]
	ds_read_b128 v[176:179], v195 offset:32768
	ds_read_b128 v[180:183], v195 offset:33792
	ds_read_b128 v[184:187], v195 offset:34816
	ds_read_b128 v[198:201], v195 offset:35840
	ds_read_b128 v[202:205], v195 offset:36864
	ds_read_b128 v[206:209], v195 offset:37888
	ds_read_b128 v[210:213], v195 offset:38912
	ds_read_b128 v[214:217], v195 offset:39936
	global_load_lds_dwordx4 v[224:225], off
	v_lshl_add_u64 v[224:225], s[58:59], 0, v[148:149]
	s_mov_b32 m0, s67
	s_nop 0
	global_load_lds_dwordx4 v[224:225], off
	s_waitcnt vmcnt(8)
	s_waitcnt lgkmcnt(0)
	s_barrier
	s_setprio 1
	s_waitcnt lgkmcnt(0)
	v_mfma_f32_16x16x32_bf16 v[142:145], v[118:121], v[176:179], v[142:145]
	v_mfma_f32_16x16x32_bf16 v[138:141], v[130:133], v[176:179], v[138:141]
	v_mfma_f32_16x16x32_bf16 v[110:113], v[118:121], v[184:187], v[110:113]
	v_mfma_f32_16x16x32_bf16 v[106:109], v[130:133], v[184:187], v[106:109]
	v_mfma_f32_16x16x32_bf16 v[94:97], v[118:121], v[202:205], v[94:97]
	v_mfma_f32_16x16x32_bf16 v[90:93], v[130:133], v[202:205], v[90:93]
	v_mfma_f32_16x16x32_bf16 v[78:81], v[118:121], v[210:213], v[78:81]
	v_mfma_f32_16x16x32_bf16 v[74:77], v[130:133], v[210:213], v[74:77]
	v_mfma_f32_16x16x32_bf16 v[142:145], v[126:129], v[180:183], v[142:145]
	v_mfma_f32_16x16x32_bf16 v[138:141], v[134:137], v[180:183], v[138:141]
	v_mfma_f32_16x16x32_bf16 v[110:113], v[126:129], v[198:201], v[110:113]
	v_mfma_f32_16x16x32_bf16 v[106:109], v[134:137], v[198:201], v[106:109]
	v_mfma_f32_16x16x32_bf16 v[94:97], v[126:129], v[206:209], v[94:97]
	v_mfma_f32_16x16x32_bf16 v[90:93], v[134:137], v[206:209], v[90:93]
	v_mfma_f32_16x16x32_bf16 v[78:81], v[126:129], v[214:217], v[78:81]
	v_mfma_f32_16x16x32_bf16 v[74:77], v[134:137], v[214:217], v[74:77]
	s_setprio 0
	s_setprio 1
	v_mfma_f32_16x16x32_bf16 v[122:125], v[160:163], v[176:179], v[122:125]
	v_mfma_f32_16x16x32_bf16 v[114:117], v[168:171], v[176:179], v[114:117]
	v_mfma_f32_16x16x32_bf16 v[102:105], v[160:163], v[184:187], v[102:105]
	v_mfma_f32_16x16x32_bf16 v[98:101], v[168:171], v[184:187], v[98:101]
	v_mfma_f32_16x16x32_bf16 v[86:89], v[160:163], v[202:205], v[86:89]
	v_mfma_f32_16x16x32_bf16 v[82:85], v[168:171], v[202:205], v[82:85]
	v_mfma_f32_16x16x32_bf16 v[70:73], v[160:163], v[210:213], v[70:73]
	v_mfma_f32_16x16x32_bf16 v[66:69], v[168:171], v[210:213], v[66:69]
	v_mfma_f32_16x16x32_bf16 v[122:125], v[164:167], v[180:183], v[122:125]
	v_mfma_f32_16x16x32_bf16 v[114:117], v[172:175], v[180:183], v[114:117]
	v_mfma_f32_16x16x32_bf16 v[102:105], v[164:167], v[198:201], v[102:105]
	v_mfma_f32_16x16x32_bf16 v[98:101], v[172:175], v[198:201], v[98:101]
	v_mfma_f32_16x16x32_bf16 v[86:89], v[164:167], v[206:209], v[86:89]
	v_mfma_f32_16x16x32_bf16 v[82:85], v[172:175], v[206:209], v[82:85]
	v_mfma_f32_16x16x32_bf16 v[70:73], v[164:167], v[214:217], v[70:73]
	v_mfma_f32_16x16x32_bf16 v[66:69], v[172:175], v[214:217], v[66:69]
	s_setprio 0
	s_barrier
	s_add_i32 s58, s62, s33
	v_lshl_add_u64 v[188:189], v[188:189], 0, s[18:19]
	s_mov_b32 m0, s58
	ds_read_b128 v[176:179], v195 offset:49152
	ds_read_b128 v[180:183], v195 offset:50176
	ds_read_b128 v[184:187], v195 offset:51200
	ds_read_b128 v[198:201], v195 offset:52224
	ds_read_b128 v[202:205], v195 offset:53248
	ds_read_b128 v[206:209], v195 offset:54272
	ds_read_b128 v[210:213], v195 offset:55296
	ds_read_b128 v[214:217], v195 offset:56320
	global_load_lds_dwordx4 v[188:189], off
	s_add_i32 m0, s58, 0x2000
	s_add_u32 s8, s8, 0x100080
	v_lshl_add_u64 v[188:189], v[218:219], 0, s[18:19]
	s_addc_u32 s9, s9, 0
	s_add_i32 s58, s63, s33
	global_load_lds_dwordx4 v[188:189], off
	v_lshl_add_u64 v[188:189], s[8:9], 0, v[146:147]
	s_mov_b32 m0, s58
	s_nop 0
	global_load_lds_dwordx4 v[188:189], off
	v_lshl_add_u64 v[188:189], s[8:9], 0, v[148:149]
	s_add_i32 m0, s58, 0x2000
	s_nop 0
	global_load_lds_dwordx4 v[188:189], off
	v_lshl_add_u64 v[188:189], v[220:221], 0, s[18:19]
	s_mov_b32 m0, s75
	s_nop 0
	global_load_lds_dwordx4 v[188:189], off
	v_lshl_add_u64 v[188:189], v[222:223], 0, s[18:19]
	s_mov_b32 m0, s76
	s_nop 0
	global_load_lds_dwordx4 v[188:189], off
	s_waitcnt vmcnt(8)
	s_waitcnt lgkmcnt(0)
	s_barrier
	s_setprio 1
	s_waitcnt lgkmcnt(0)
	v_mfma_f32_16x16x32_bf16 v[58:61], v[118:121], v[176:179], v[58:61]
	v_mfma_f32_16x16x32_bf16 v[62:65], v[130:133], v[176:179], v[62:65]
	v_mfma_f32_16x16x32_bf16 v[46:49], v[118:121], v[184:187], v[46:49]
	v_mfma_f32_16x16x32_bf16 v[42:45], v[130:133], v[184:187], v[42:45]
	v_mfma_f32_16x16x32_bf16 v[30:33], v[118:121], v[202:205], v[30:33]
	v_mfma_f32_16x16x32_bf16 v[26:29], v[130:133], v[202:205], v[26:29]
	v_mfma_f32_16x16x32_bf16 v[14:17], v[118:121], v[210:213], v[14:17]
	v_mfma_f32_16x16x32_bf16 v[10:13], v[130:133], v[210:213], v[10:13]
	v_mfma_f32_16x16x32_bf16 v[58:61], v[126:129], v[180:183], v[58:61]
	v_mfma_f32_16x16x32_bf16 v[62:65], v[134:137], v[180:183], v[62:65]
	v_mfma_f32_16x16x32_bf16 v[46:49], v[126:129], v[198:201], v[46:49]
	v_mfma_f32_16x16x32_bf16 v[42:45], v[134:137], v[198:201], v[42:45]
	v_mfma_f32_16x16x32_bf16 v[30:33], v[126:129], v[206:209], v[30:33]
	v_mfma_f32_16x16x32_bf16 v[26:29], v[134:137], v[206:209], v[26:29]
	v_mfma_f32_16x16x32_bf16 v[14:17], v[126:129], v[214:217], v[14:17]
	v_mfma_f32_16x16x32_bf16 v[10:13], v[134:137], v[214:217], v[10:13]
	s_setprio 0
	s_setprio 1
	v_mfma_f32_16x16x32_bf16 v[54:57], v[160:163], v[176:179], v[54:57]
	v_mfma_f32_16x16x32_bf16 v[50:53], v[168:171], v[176:179], v[50:53]
	v_mfma_f32_16x16x32_bf16 v[38:41], v[160:163], v[184:187], v[38:41]
	v_mfma_f32_16x16x32_bf16 v[34:37], v[168:171], v[184:187], v[34:37]
	v_mfma_f32_16x16x32_bf16 v[22:25], v[160:163], v[202:205], v[22:25]
	v_mfma_f32_16x16x32_bf16 v[18:21], v[168:171], v[202:205], v[18:21]
	v_mfma_f32_16x16x32_bf16 v[6:9], v[160:163], v[210:213], v[6:9]
	v_mfma_f32_16x16x32_bf16 v[2:5], v[168:171], v[210:213], v[2:5]
	v_mfma_f32_16x16x32_bf16 v[54:57], v[164:167], v[180:183], v[54:57]
	v_mfma_f32_16x16x32_bf16 v[50:53], v[172:175], v[180:183], v[50:53]
	v_mfma_f32_16x16x32_bf16 v[38:41], v[164:167], v[198:201], v[38:41]
	v_mfma_f32_16x16x32_bf16 v[34:37], v[172:175], v[198:201], v[34:37]
	v_mfma_f32_16x16x32_bf16 v[22:25], v[164:167], v[206:209], v[22:25]
	v_mfma_f32_16x16x32_bf16 v[18:21], v[172:175], v[206:209], v[18:21]
	v_mfma_f32_16x16x32_bf16 v[6:9], v[164:167], v[214:217], v[6:9]
	v_mfma_f32_16x16x32_bf16 v[2:5], v[172:175], v[214:217], v[2:5]
	s_setprio 0
	s_barrier
	s_add_i32 s61, s61, 2
	s_add_u32 s4, s4, 0x100
	s_addc_u32 s5, s5, 0
	s_add_u32 s57, s57, 0x100
	s_addc_u32 s60, s60, 0
	s_cmp_gt_u32 s61, 61
	s_cbranch_scc0 .LBB0_855
	s_branch .Lrwp7_exit
